# GEMM K-loops (all 7 sites): LDS-DMA tile loads use 32-bit lane offset + scalar base (saddr form) instead of per-load v_lshl_add_u64 64-bit lane address; 16 VALU 64-bit adds removed per K iteration
# speedup vs baseline: 1.0105x; 1.0038x over previous
; #define PG8_STAGE(bufoff, gbase, voff) do { _Pragma("unroll") for (int _i = 0; _i < 2; ++_i) \
;         __builtin_amdgcn_global_load_lds((const unsigned*)((const char*)(gbase) + (voff)[_i]), (PG8_LAS unsigned*)(lds + (bufoff) + ldsw + _i * 8192), 16, 0, 0); } while (0)
; #define PG8_LDA(dst, b, h) do { _Pragma("unroll") for (int m = 0; m < 4; ++m) _Pragma("unroll") for (int k = 0; k < 2; ++k) dst[m][k] = *(const PG8_LAS bf16x8*)(lds + PG8_SA(b, h) + aoff + m * 2048 + k * 1024); } while (0)
; #define PG8_LDB(dst, b, h) do { _Pragma("unroll") for (int n = 0; n < 2; ++n) _Pragma("unroll") for (int k = 0; k < 2; ++k) dst[n][k] = *(const PG8_LAS bf16x8*)(lds + PG8_SB(b, h) + boff + n * 2048 + k * 1024); } while (0)
; #define PG8_MMA(ai, bj, At, Bt) do { __builtin_amdgcn_s_setprio(1); _Pragma("unroll") for (int m = 0; m < 4; ++m) _Pragma("unroll") for (int n = 0; n < 2; ++n) _Pragma("unroll") for (int k = 0; k < 2; ++k) \
;         acc[ai][bj][m][n] = __builtin_amdgcn_mfma_f32_16x16x32_bf16(Bt[n][k], At[m][k], acc[ai][bj][m][n], 0, 0, 0); __builtin_amdgcn_s_setprio(0); } while (0)
; #define PG8_WAIT_V(n) asm volatile("s_waitcnt vmcnt(" #n ")" ::: "memory")
; #define PG8_BAR __builtin_amdgcn_s_barrier()
; template <class Epi, class Sched, bool ALIGN_EPI = false, bool SP2 = false>
; __device__ __forceinline__ void gemm_phase(PG8_LAS unsigned char* lds, const Gemm g, const Sched& S, const Epi& E) {
;     ...
;         for (int t = 0; t < nt; t += 2) {
;             const bool last = (t == nt - 2);
;             const char* a1 = cA + (size_t)(t + 1) * kstep;
;             const char* a2 = last ? nA : cA + (size_t)(t + 2) * kstep; const char* b2 = last ? nB : cB + (size_t)(t + 2) * kstep;
;             const char* a3 = a2 + kstep; const char* b3 = b2 + kstep;
;             if (last && has_next) S.a_ready(nxt);
;             if constexpr (SP2) {
;             PG8_LDB(B0, 0, 0); PG8_LDB(B1, 0, 1); PG8_SCHED; PG8_LDA(At, 0, 0); PG8_STAGE(PG8_SA(1, 1), a1 + hstep, voffA);
;             PG8_WAIT_V(8); PG8_WAIT_L(0); PG8_BAR; PG8_MMA(0, 0, At, B0); PG8_MMA(0, 1, At, B1); PG8_BAR; PG8_SCHED;
;             PG8_LDA(At, 0, 1); PG8_STAGE(PG8_SB(0, 0), b2, voffB); PG8_STAGE(PG8_SB(0, 1), b2 + hstep, voffB); PG8_STAGE(PG8_SA(0, 0), a2, voffA);
;             PG8_WAIT_V(8); PG8_WAIT_L(0); PG8_BAR; PG8_MMA(1, 0, At, B0); PG8_MMA(1, 1, At, B1); PG8_BAR; PG8_SCHED;
.LBB0_208:
	s_add_i32 s59, s33, 2
	s_add_u32 s6, s30, 0x80
	s_addc_u32 s7, s31, 0
	s_add_i32 s67, 0, 0x10000
	s_cmp_eq_u32 s60, s33
	s_cselect_b32 s35, s11, s7
	s_cselect_b32 s34, s10, s6
	v_add_u32_e32 v150, s67, v158
	s_cselect_b32 s7, s29, s54
	s_cselect_b32 s6, s28, s2
	s_add_i32 s33, 0, 0x14000
	ds_read_b128 v[146:149], v150
	ds_read_b128 v[162:165], v150 offset:1024
	ds_read_b128 v[166:169], v150 offset:2048
	ds_read_b128 v[170:173], v150 offset:3072
	v_add_u32_e32 v150, s33, v158
	ds_read_b128 v[174:177], v150
	ds_read_b128 v[182:185], v150 offset:1024
	ds_read_b128 v[186:189], v150 offset:2048
	ds_read_b128 v[190:193], v150 offset:3072
	s_add_i32 m0, s47, 0xc000
	ds_read_b128 v[194:197], v160
	ds_read_b128 v[198:201], v160 offset:1024
	ds_read_b128 v[202:205], v160 offset:2048
	ds_read_b128 v[206:209], v160 offset:3072
	ds_read_b128 v[210:213], v160 offset:4096
	ds_read_b128 v[214:217], v160 offset:5120
	ds_read_b128 v[218:221], v160 offset:6144
	ds_read_b128 v[222:225], v160 offset:7168
	global_load_lds_dwordx4 v140, s[30:31]
	s_add_i32 m0, s47, 0xe000
	s_nop 0
	global_load_lds_dwordx4 v142, s[30:31]
	s_waitcnt vmcnt(8)
	s_waitcnt lgkmcnt(0)
	s_barrier
	s_setprio 1
	s_waitcnt lgkmcnt(0)
	v_mfma_f32_16x16x32_bf16 v[122:125], v[146:149], v[194:197], v[122:125]
	v_mfma_f32_16x16x32_bf16 v[126:129], v[166:169], v[194:197], v[126:129]
	v_mfma_f32_16x16x32_bf16 v[110:113], v[146:149], v[202:205], v[110:113]
	v_mfma_f32_16x16x32_bf16 v[106:109], v[166:169], v[202:205], v[106:109]
	v_mfma_f32_16x16x32_bf16 v[94:97], v[146:149], v[210:213], v[94:97]
	v_mfma_f32_16x16x32_bf16 v[90:93], v[166:169], v[210:213], v[90:93]
	v_mfma_f32_16x16x32_bf16 v[78:81], v[146:149], v[218:221], v[78:81]
	v_mfma_f32_16x16x32_bf16 v[74:77], v[166:169], v[218:221], v[74:77]
	v_mfma_f32_16x16x32_bf16 v[122:125], v[162:165], v[198:201], v[122:125]
	v_mfma_f32_16x16x32_bf16 v[126:129], v[170:173], v[198:201], v[126:129]
	v_mfma_f32_16x16x32_bf16 v[110:113], v[162:165], v[206:209], v[110:113]
	v_mfma_f32_16x16x32_bf16 v[106:109], v[170:173], v[206:209], v[106:109]
	v_mfma_f32_16x16x32_bf16 v[94:97], v[162:165], v[214:217], v[94:97]
	v_mfma_f32_16x16x32_bf16 v[90:93], v[170:173], v[214:217], v[90:93]
	v_mfma_f32_16x16x32_bf16 v[78:81], v[162:165], v[222:225], v[78:81]
	v_mfma_f32_16x16x32_bf16 v[74:77], v[170:173], v[222:225], v[74:77]
	s_setprio 0
	s_setprio 1
	v_mfma_f32_16x16x32_bf16 v[118:121], v[174:177], v[194:197], v[118:121]
	v_mfma_f32_16x16x32_bf16 v[114:117], v[186:189], v[194:197], v[114:117]
	v_mfma_f32_16x16x32_bf16 v[102:105], v[174:177], v[202:205], v[102:105]
	v_mfma_f32_16x16x32_bf16 v[98:101], v[186:189], v[202:205], v[98:101]
	v_mfma_f32_16x16x32_bf16 v[86:89], v[174:177], v[210:213], v[86:89]
	v_mfma_f32_16x16x32_bf16 v[82:85], v[186:189], v[210:213], v[82:85]
	v_mfma_f32_16x16x32_bf16 v[70:73], v[174:177], v[218:221], v[70:73]
	v_mfma_f32_16x16x32_bf16 v[66:69], v[186:189], v[218:221], v[66:69]
	v_mfma_f32_16x16x32_bf16 v[118:121], v[182:185], v[198:201], v[118:121]
	v_mfma_f32_16x16x32_bf16 v[114:117], v[190:193], v[198:201], v[114:117]
	v_mfma_f32_16x16x32_bf16 v[102:105], v[182:185], v[206:209], v[102:105]
	v_mfma_f32_16x16x32_bf16 v[98:101], v[190:193], v[206:209], v[98:101]
	v_mfma_f32_16x16x32_bf16 v[86:89], v[182:185], v[214:217], v[86:89]
	v_mfma_f32_16x16x32_bf16 v[82:85], v[190:193], v[214:217], v[82:85]
	v_mfma_f32_16x16x32_bf16 v[70:73], v[182:185], v[222:225], v[70:73]
	v_mfma_f32_16x16x32_bf16 v[66:69], v[190:193], v[222:225], v[66:69]
	s_setprio 0
	s_barrier
	s_add_i32 s67, s67, s41
	s_mov_b32 m0, s67
	ds_read_b128 v[194:197], v160 offset:16384
	ds_read_b128 v[198:201], v160 offset:17408
	ds_read_b128 v[202:205], v160 offset:18432
	ds_read_b128 v[206:209], v160 offset:19456
	ds_read_b128 v[210:213], v160 offset:20480
	ds_read_b128 v[214:217], v160 offset:21504
	ds_read_b128 v[218:221], v160 offset:22528
	ds_read_b128 v[222:225], v160 offset:23552
	global_load_lds_dwordx4 v134, s[6:7]
	s_add_i32 m0, s67, 0x2000
	s_add_u32 s100, s6, 0x80
	s_addc_u32 s101, s7, 0
	global_load_lds_dwordx4 v130, s[6:7]
	s_add_u32 s6, s6, s14
	s_addc_u32 s7, s7, s15
	s_add_i32 s33, s33, s41
	s_mov_b32 m0, s33
	s_nop 0
	global_load_lds_dwordx4 v134, s[6:7]
	s_add_i32 m0, s33, 0x2000
	s_nop 0
	global_load_lds_dwordx4 v130, s[6:7]
	s_mov_b32 m0, s47
	s_nop 0
	global_load_lds_dwordx4 v136, s[34:35]
	s_mov_b32 m0, s48
	s_nop 0
	global_load_lds_dwordx4 v132, s[34:35]
	s_waitcnt vmcnt(8)
	s_waitcnt lgkmcnt(0)
	s_barrier
	s_setprio 1
	s_waitcnt lgkmcnt(0)
	v_mfma_f32_16x16x32_bf16 v[62:65], v[146:149], v[194:197], v[62:65]
	v_mfma_f32_16x16x32_bf16 v[58:61], v[166:169], v[194:197], v[58:61]
	v_mfma_f32_16x16x32_bf16 v[46:49], v[146:149], v[202:205], v[46:49]
	v_mfma_f32_16x16x32_bf16 v[42:45], v[166:169], v[202:205], v[42:45]
	v_mfma_f32_16x16x32_bf16 v[30:33], v[146:149], v[210:213], v[30:33]
	v_mfma_f32_16x16x32_bf16 v[26:29], v[166:169], v[210:213], v[26:29]
	v_mfma_f32_16x16x32_bf16 v[14:17], v[146:149], v[218:221], v[14:17]
	v_mfma_f32_16x16x32_bf16 v[10:13], v[166:169], v[218:221], v[10:13]
	v_mfma_f32_16x16x32_bf16 v[62:65], v[162:165], v[198:201], v[62:65]
	v_mfma_f32_16x16x32_bf16 v[58:61], v[170:173], v[198:201], v[58:61]
	v_mfma_f32_16x16x32_bf16 v[46:49], v[162:165], v[206:209], v[46:49]
	v_mfma_f32_16x16x32_bf16 v[42:45], v[170:173], v[206:209], v[42:45]
	v_mfma_f32_16x16x32_bf16 v[30:33], v[162:165], v[214:217], v[30:33]
	v_mfma_f32_16x16x32_bf16 v[26:29], v[170:173], v[214:217], v[26:29]
	v_mfma_f32_16x16x32_bf16 v[14:17], v[162:165], v[222:225], v[14:17]
	v_mfma_f32_16x16x32_bf16 v[10:13], v[170:173], v[222:225], v[10:13]
	s_setprio 0
	s_setprio 1
	v_mfma_f32_16x16x32_bf16 v[54:57], v[174:177], v[194:197], v[54:57]
	v_mfma_f32_16x16x32_bf16 v[50:53], v[186:189], v[194:197], v[50:53]
	v_mfma_f32_16x16x32_bf16 v[38:41], v[174:177], v[202:205], v[38:41]
	v_mfma_f32_16x16x32_bf16 v[34:37], v[186:189], v[202:205], v[34:37]
	v_mfma_f32_16x16x32_bf16 v[22:25], v[174:177], v[210:213], v[22:25]
	v_mfma_f32_16x16x32_bf16 v[18:21], v[186:189], v[210:213], v[18:21]
	v_mfma_f32_16x16x32_bf16 v[6:9], v[174:177], v[218:221], v[6:9]
	v_mfma_f32_16x16x32_bf16 v[2:5], v[186:189], v[218:221], v[2:5]
	v_mfma_f32_16x16x32_bf16 v[54:57], v[182:185], v[198:201], v[54:57]
	v_mfma_f32_16x16x32_bf16 v[50:53], v[190:193], v[198:201], v[50:53]
	v_mfma_f32_16x16x32_bf16 v[38:41], v[182:185], v[206:209], v[38:41]
	v_mfma_f32_16x16x32_bf16 v[34:37], v[190:193], v[206:209], v[34:37]
	v_mfma_f32_16x16x32_bf16 v[22:25], v[182:185], v[214:217], v[22:25]
	v_mfma_f32_16x16x32_bf16 v[18:21], v[190:193], v[214:217], v[18:21]
	v_mfma_f32_16x16x32_bf16 v[6:9], v[182:185], v[222:225], v[6:9]
	v_mfma_f32_16x16x32_bf16 v[2:5], v[190:193], v[222:225], v[2:5]
	s_setprio 0
	s_barrier
; #define PG8_STAGE(bufoff, gbase, voff) do { _Pragma("unroll") for (int _i = 0; _i < 2; ++_i) \
;         __builtin_amdgcn_global_load_lds((const unsigned*)((const char*)(gbase) + (voff)[_i]), (PG8_LAS unsigned*)(lds + (bufoff) + ldsw + _i * 8192), 16, 0, 0); } while (0)
; #define PG8_LDA(dst, b, h) do { _Pragma("unroll") for (int m = 0; m < 4; ++m) _Pragma("unroll") for (int k = 0; k < 2; ++k) dst[m][k] = *(const PG8_LAS bf16x8*)(lds + PG8_SA(b, h) + aoff + m * 2048 + k * 1024); } while (0)
; #define PG8_LDB(dst, b, h) do { _Pragma("unroll") for (int n = 0; n < 2; ++n) _Pragma("unroll") for (int k = 0; k < 2; ++k) dst[n][k] = *(const PG8_LAS bf16x8*)(lds + PG8_SB(b, h) + boff + n * 2048 + k * 1024); } while (0)
; #define PG8_WAIT_V(n) asm volatile("s_waitcnt vmcnt(" #n ")" ::: "memory")
; #define PG8_WAIT_L(n) asm volatile("s_waitcnt lgkmcnt(" #n ")" ::: "memory")
; template <class Epi, class Sched, bool ALIGN_EPI = false, bool SP2 = false>
; __device__ __forceinline__ void gemm_phase(PG8_LAS unsigned char* lds, const Gemm g, const Sched& S, const Epi& E) {
;     ...
;             const char* a2 = last ? nA : cA + (size_t)(t + 2) * kstep; const char* b2 = last ? nB : cB + (size_t)(t + 2) * kstep;
;             const char* a3 = a2 + kstep; const char* b3 = b2 + kstep;
;             if (last && has_next) S.a_ready(nxt);
;             if constexpr (SP2) {
;             PG8_LDB(B0, 0, 0); PG8_LDB(B1, 0, 1); PG8_SCHED; PG8_LDA(At, 0, 0); PG8_STAGE(PG8_SA(1, 1), a1 + hstep, voffA);
;             PG8_WAIT_V(8); PG8_WAIT_L(0); PG8_BAR; PG8_MMA(0, 0, At, B0); PG8_MMA(0, 1, At, B1); PG8_BAR; PG8_SCHED;
;             PG8_LDA(At, 0, 1); PG8_STAGE(PG8_SB(0, 0), b2, voffB); PG8_STAGE(PG8_SB(0, 1), b2 + hstep, voffB); PG8_STAGE(PG8_SA(0, 0), a2, voffA);
;             PG8_WAIT_V(8); PG8_WAIT_L(0); PG8_BAR; PG8_MMA(1, 0, At, B0); PG8_MMA(1, 1, At, B1); PG8_BAR; PG8_SCHED;
;             PG8_LDB(B0, 1, 0); PG8_LDB(B1, 1, 1); PG8_SCHED; PG8_LDA(At, 1, 0); PG8_STAGE(PG8_SA(0, 1), a2 + hstep, voffA);
;             PG8_WAIT_V(8); PG8_WAIT_L(0); PG8_BAR; PG8_MMA(0, 0, At, B0); PG8_MMA(0, 1, At, B1); PG8_BAR; PG8_SCHED;
;             PG8_LDA(At, 1, 1); PG8_STAGE(PG8_SB(1, 0), b3, voffB); PG8_STAGE(PG8_SB(1, 1), b3 + hstep, voffB); PG8_STAGE(PG8_SA(1, 0), a3, voffA);
;             PG8_WAIT_V(8); PG8_WAIT_L(0); PG8_BAR; PG8_MMA(1, 0, At, B0); PG8_MMA(1, 1, At, B1); PG8_BAR; PG8_SCHED;
	s_add_i32 s33, 0, 0x18000
	v_add_u32_e32 v161, s33, v158
	s_add_i32 s67, 0, 0x1c000
	ds_read_b128 v[146:149], v161
	ds_read_b128 v[162:165], v161 offset:1024
	ds_read_b128 v[166:169], v161 offset:2048
	ds_read_b128 v[170:173], v161 offset:3072
	v_add_u32_e32 v161, s67, v158
	ds_read_b128 v[174:177], v161
	ds_read_b128 v[182:185], v161 offset:1024
	ds_read_b128 v[186:189], v161 offset:2048
	ds_read_b128 v[190:193], v161 offset:3072
	s_add_u32 s6, s34, s14
	s_addc_u32 s7, s35, s15
	s_mov_b32 m0, s49
	ds_read_b128 v[194:197], v160 offset:32768
	ds_read_b128 v[198:201], v160 offset:33792
	ds_read_b128 v[202:205], v160 offset:34816
	ds_read_b128 v[206:209], v160 offset:35840
	ds_read_b128 v[210:213], v160 offset:36864
	ds_read_b128 v[214:217], v160 offset:37888
	ds_read_b128 v[218:221], v160 offset:38912
	ds_read_b128 v[222:225], v160 offset:39936
	global_load_lds_dwordx4 v136, s[6:7]
	s_mov_b32 m0, s50
	s_nop 0
	global_load_lds_dwordx4 v132, s[6:7]
	s_waitcnt vmcnt(8)
	s_waitcnt lgkmcnt(0)
	s_barrier
	s_setprio 1
	s_waitcnt lgkmcnt(0)
	v_mfma_f32_16x16x32_bf16 v[122:125], v[146:149], v[194:197], v[122:125]
	v_mfma_f32_16x16x32_bf16 v[126:129], v[166:169], v[194:197], v[126:129]
	v_mfma_f32_16x16x32_bf16 v[110:113], v[146:149], v[202:205], v[110:113]
	v_mfma_f32_16x16x32_bf16 v[106:109], v[166:169], v[202:205], v[106:109]
	v_mfma_f32_16x16x32_bf16 v[94:97], v[146:149], v[210:213], v[94:97]
	v_mfma_f32_16x16x32_bf16 v[90:93], v[166:169], v[210:213], v[90:93]
	v_mfma_f32_16x16x32_bf16 v[78:81], v[146:149], v[218:221], v[78:81]
	v_mfma_f32_16x16x32_bf16 v[74:77], v[166:169], v[218:221], v[74:77]
	v_mfma_f32_16x16x32_bf16 v[122:125], v[162:165], v[198:201], v[122:125]
	v_mfma_f32_16x16x32_bf16 v[126:129], v[170:173], v[198:201], v[126:129]
	v_mfma_f32_16x16x32_bf16 v[110:113], v[162:165], v[206:209], v[110:113]
	v_mfma_f32_16x16x32_bf16 v[106:109], v[170:173], v[206:209], v[106:109]
	v_mfma_f32_16x16x32_bf16 v[94:97], v[162:165], v[214:217], v[94:97]
	v_mfma_f32_16x16x32_bf16 v[90:93], v[170:173], v[214:217], v[90:93]
	v_mfma_f32_16x16x32_bf16 v[78:81], v[162:165], v[222:225], v[78:81]
	v_mfma_f32_16x16x32_bf16 v[74:77], v[170:173], v[222:225], v[74:77]
	s_setprio 0
	s_setprio 1
	v_mfma_f32_16x16x32_bf16 v[118:121], v[174:177], v[194:197], v[118:121]
	v_mfma_f32_16x16x32_bf16 v[114:117], v[186:189], v[194:197], v[114:117]
	v_mfma_f32_16x16x32_bf16 v[102:105], v[174:177], v[202:205], v[102:105]
	v_mfma_f32_16x16x32_bf16 v[98:101], v[186:189], v[202:205], v[98:101]
	v_mfma_f32_16x16x32_bf16 v[86:89], v[174:177], v[210:213], v[86:89]
	v_mfma_f32_16x16x32_bf16 v[82:85], v[186:189], v[210:213], v[82:85]
	v_mfma_f32_16x16x32_bf16 v[70:73], v[174:177], v[218:221], v[70:73]
	v_mfma_f32_16x16x32_bf16 v[66:69], v[186:189], v[218:221], v[66:69]
	v_mfma_f32_16x16x32_bf16 v[118:121], v[182:185], v[198:201], v[118:121]
	v_mfma_f32_16x16x32_bf16 v[114:117], v[190:193], v[198:201], v[114:117]
	v_mfma_f32_16x16x32_bf16 v[102:105], v[182:185], v[206:209], v[102:105]
	v_mfma_f32_16x16x32_bf16 v[98:101], v[190:193], v[206:209], v[98:101]
	v_mfma_f32_16x16x32_bf16 v[86:89], v[182:185], v[214:217], v[86:89]
	v_mfma_f32_16x16x32_bf16 v[82:85], v[190:193], v[214:217], v[82:85]
	v_mfma_f32_16x16x32_bf16 v[70:73], v[182:185], v[222:225], v[70:73]
	v_mfma_f32_16x16x32_bf16 v[66:69], v[190:193], v[222:225], v[66:69]
	s_setprio 0
	s_barrier
	s_add_i32 s6, s33, s41
	s_mov_b32 m0, s6
	ds_read_b128 v[194:197], v160 offset:49152
	ds_read_b128 v[198:201], v160 offset:50176
	ds_read_b128 v[202:205], v160 offset:51200
	ds_read_b128 v[206:209], v160 offset:52224
	ds_read_b128 v[210:213], v160 offset:53248
	ds_read_b128 v[214:217], v160 offset:54272
	ds_read_b128 v[218:221], v160 offset:55296
	ds_read_b128 v[222:225], v160 offset:56320
	global_load_lds_dwordx4 v134, s[100:101]
	s_add_i32 m0, s6, 0x2000
	s_add_i32 s6, s67, s41
	global_load_lds_dwordx4 v130, s[100:101]
	s_add_u32 s100, s100, s14
	s_addc_u32 s101, s101, s15
	s_mov_b32 m0, s6
	s_nop 0
	global_load_lds_dwordx4 v134, s[100:101]
	s_add_i32 m0, s6, 0x2000
	s_nop 0
	global_load_lds_dwordx4 v130, s[100:101]
	s_add_u32 s100, s34, 0x80
	s_addc_u32 s101, s35, 0
	s_mov_b32 m0, s56
	s_nop 0
	global_load_lds_dwordx4 v136, s[100:101]
	s_mov_b32 m0, s57
	s_nop 0
	global_load_lds_dwordx4 v132, s[100:101]
	s_waitcnt vmcnt(8)
	s_waitcnt lgkmcnt(0)
	s_barrier
	s_setprio 1
	s_waitcnt lgkmcnt(0)
	v_mfma_f32_16x16x32_bf16 v[62:65], v[146:149], v[194:197], v[62:65]
	v_mfma_f32_16x16x32_bf16 v[58:61], v[166:169], v[194:197], v[58:61]
	v_mfma_f32_16x16x32_bf16 v[46:49], v[146:149], v[202:205], v[46:49]
	v_mfma_f32_16x16x32_bf16 v[42:45], v[166:169], v[202:205], v[42:45]
	v_mfma_f32_16x16x32_bf16 v[30:33], v[146:149], v[210:213], v[30:33]
	v_mfma_f32_16x16x32_bf16 v[26:29], v[166:169], v[210:213], v[26:29]
	v_mfma_f32_16x16x32_bf16 v[14:17], v[146:149], v[218:221], v[14:17]
	v_mfma_f32_16x16x32_bf16 v[10:13], v[166:169], v[218:221], v[10:13]
	v_mfma_f32_16x16x32_bf16 v[62:65], v[162:165], v[198:201], v[62:65]
	v_mfma_f32_16x16x32_bf16 v[58:61], v[170:173], v[198:201], v[58:61]
	v_mfma_f32_16x16x32_bf16 v[46:49], v[162:165], v[206:209], v[46:49]
	v_mfma_f32_16x16x32_bf16 v[42:45], v[170:173], v[206:209], v[42:45]
	v_mfma_f32_16x16x32_bf16 v[30:33], v[162:165], v[214:217], v[30:33]
	v_mfma_f32_16x16x32_bf16 v[26:29], v[170:173], v[214:217], v[26:29]
	v_mfma_f32_16x16x32_bf16 v[14:17], v[162:165], v[222:225], v[14:17]
	v_mfma_f32_16x16x32_bf16 v[10:13], v[170:173], v[222:225], v[10:13]
	s_setprio 0
	s_setprio 1
	v_mfma_f32_16x16x32_bf16 v[54:57], v[174:177], v[194:197], v[54:57]
	v_mfma_f32_16x16x32_bf16 v[50:53], v[186:189], v[194:197], v[50:53]
	v_mfma_f32_16x16x32_bf16 v[38:41], v[174:177], v[202:205], v[38:41]
	v_mfma_f32_16x16x32_bf16 v[34:37], v[186:189], v[202:205], v[34:37]
	v_mfma_f32_16x16x32_bf16 v[22:25], v[174:177], v[210:213], v[22:25]
	v_mfma_f32_16x16x32_bf16 v[18:21], v[186:189], v[210:213], v[18:21]
	v_mfma_f32_16x16x32_bf16 v[6:9], v[174:177], v[218:221], v[6:9]
	v_mfma_f32_16x16x32_bf16 v[2:5], v[186:189], v[218:221], v[2:5]
	v_mfma_f32_16x16x32_bf16 v[54:57], v[182:185], v[198:201], v[54:57]
	v_mfma_f32_16x16x32_bf16 v[50:53], v[190:193], v[198:201], v[50:53]
	v_mfma_f32_16x16x32_bf16 v[38:41], v[182:185], v[206:209], v[38:41]
	v_mfma_f32_16x16x32_bf16 v[34:37], v[190:193], v[206:209], v[34:37]
	v_mfma_f32_16x16x32_bf16 v[22:25], v[182:185], v[214:217], v[22:25]
	v_mfma_f32_16x16x32_bf16 v[18:21], v[190:193], v[214:217], v[18:21]
	v_mfma_f32_16x16x32_bf16 v[6:9], v[182:185], v[222:225], v[6:9]
	v_mfma_f32_16x16x32_bf16 v[2:5], v[190:193], v[222:225], v[2:5]
	s_setprio 0
	s_barrier
	s_add_u32 s30, s30, 0x100
	s_addc_u32 s31, s31, 0
	s_add_u32 s2, s2, 0x100
	s_addc_u32 s54, s54, 0
	s_cmp_ge_i32 s59, s51
	s_mov_b32 s33, s59
	s_cbranch_scc0 .LBB0_208

; #define PG8_STAGE(bufoff, gbase, voff) do { _Pragma("unroll") for (int _i = 0; _i < 2; ++_i) \
;         __builtin_amdgcn_global_load_lds((const unsigned*)((const char*)(gbase) + (voff)[_i]), (PG8_LAS unsigned*)(lds + (bufoff) + ldsw + _i * 8192), 16, 0, 0); } while (0)
; #define PG8_LDA(dst, b, h) do { _Pragma("unroll") for (int m = 0; m < 4; ++m) _Pragma("unroll") for (int k = 0; k < 2; ++k) dst[m][k] = *(const PG8_LAS bf16x8*)(lds + PG8_SA(b, h) + aoff + m * 2048 + k * 1024); } while (0)
; #define PG8_LDB(dst, b, h) do { _Pragma("unroll") for (int n = 0; n < 2; ++n) _Pragma("unroll") for (int k = 0; k < 2; ++k) dst[n][k] = *(const PG8_LAS bf16x8*)(lds + PG8_SB(b, h) + boff + n * 2048 + k * 1024); } while (0)
; #define PG8_MMA(ai, bj, At, Bt) do { __builtin_amdgcn_s_setprio(1); _Pragma("unroll") for (int m = 0; m < 4; ++m) _Pragma("unroll") for (int n = 0; n < 2; ++n) _Pragma("unroll") for (int k = 0; k < 2; ++k) \
;         acc[ai][bj][m][n] = __builtin_amdgcn_mfma_f32_16x16x32_bf16(Bt[n][k], At[m][k], acc[ai][bj][m][n], 0, 0, 0); __builtin_amdgcn_s_setprio(0); } while (0)
; #define PG8_WAIT_V(n) asm volatile("s_waitcnt vmcnt(" #n ")" ::: "memory")
; #define PG8_BAR __builtin_amdgcn_s_barrier()
; template <class Epi, class Sched, bool ALIGN_EPI = false, bool SP2 = false>
; __device__ __forceinline__ void gemm_phase(PG8_LAS unsigned char* lds, const Gemm g, const Sched& S, const Epi& E) {
;     ...
;         for (int t = 0; t < nt; t += 2) {
;             const bool last = (t == nt - 2);
;             const char* a1 = cA + (size_t)(t + 1) * kstep;
;             const char* a2 = last ? nA : cA + (size_t)(t + 2) * kstep; const char* b2 = last ? nB : cB + (size_t)(t + 2) * kstep;
;             const char* a3 = a2 + kstep; const char* b3 = b2 + kstep;
;             if (last && has_next) S.a_ready(nxt);
;             if constexpr (SP2) {
;             PG8_LDB(B0, 0, 0); PG8_LDB(B1, 0, 1); PG8_SCHED; PG8_LDA(At, 0, 0); PG8_STAGE(PG8_SA(1, 1), a1 + hstep, voffA);
;             PG8_WAIT_V(8); PG8_WAIT_L(0); PG8_BAR; PG8_MMA(0, 0, At, B0); PG8_MMA(0, 1, At, B1); PG8_BAR; PG8_SCHED;
;             PG8_LDA(At, 0, 1); PG8_STAGE(PG8_SB(0, 0), b2, voffB); PG8_STAGE(PG8_SB(0, 1), b2 + hstep, voffB); PG8_STAGE(PG8_SA(0, 0), a2, voffA);
;             PG8_WAIT_V(8); PG8_WAIT_L(0); PG8_BAR; PG8_MMA(1, 0, At, B0); PG8_MMA(1, 1, At, B1); PG8_BAR; PG8_SCHED;
.LBB0_300:
	s_add_i32 s59, s33, 2
	s_add_u32 s6, s38, 0x80
	s_addc_u32 s7, s39, 0
	s_add_i32 s72, 0, 0x10000
	s_cmp_eq_u32 s54, s33
	s_cselect_b32 s41, s13, s7
	s_cselect_b32 s40, s12, s6
	s_cselect_b32 s7, s37, s80
	s_cselect_b32 s6, s36, s79
	s_add_i32 s33, 0, 0x14000
	v_add_u32_e32 v166, s72, v148
	v_add_u32_e32 v178, s33, v148
	ds_read_b128 v[144:147], v166
	ds_read_b128 v[158:161], v166 offset:1024
	ds_read_b128 v[162:165], v166 offset:2048
	ds_read_b128 v[166:169], v166 offset:3072
	ds_read_b128 v[170:173], v178
	ds_read_b128 v[174:177], v178 offset:1024
	ds_read_b128 v[182:185], v178 offset:2048
	ds_read_b128 v[186:189], v178 offset:3072
	s_add_i32 m0, s45, 0xc000
	ds_read_b128 v[190:193], v151
	ds_read_b128 v[194:197], v151 offset:1024
	ds_read_b128 v[198:201], v151 offset:2048
	ds_read_b128 v[202:205], v151 offset:3072
	ds_read_b128 v[206:209], v151 offset:4096
	ds_read_b128 v[210:213], v151 offset:5120
	ds_read_b128 v[214:217], v151 offset:6144
	ds_read_b128 v[218:221], v151 offset:7168
	global_load_lds_dwordx4 v140, s[38:39]
	s_add_i32 m0, s45, 0xe000
	s_nop 0
	global_load_lds_dwordx4 v142, s[38:39]
	s_waitcnt vmcnt(8)
	s_waitcnt lgkmcnt(0)
	s_barrier
	s_setprio 1
	s_waitcnt lgkmcnt(0)
	v_mfma_f32_16x16x32_bf16 v[126:129], v[144:147], v[190:193], v[126:129]
	v_mfma_f32_16x16x32_bf16 v[122:125], v[162:165], v[190:193], v[122:125]
	v_mfma_f32_16x16x32_bf16 v[110:113], v[144:147], v[198:201], v[110:113]
	v_mfma_f32_16x16x32_bf16 v[106:109], v[162:165], v[198:201], v[106:109]
	v_mfma_f32_16x16x32_bf16 v[94:97], v[144:147], v[206:209], v[94:97]
	v_mfma_f32_16x16x32_bf16 v[90:93], v[162:165], v[206:209], v[90:93]
	v_mfma_f32_16x16x32_bf16 v[78:81], v[144:147], v[214:217], v[78:81]
	v_mfma_f32_16x16x32_bf16 v[74:77], v[162:165], v[214:217], v[74:77]
	v_mfma_f32_16x16x32_bf16 v[126:129], v[158:161], v[194:197], v[126:129]
	v_mfma_f32_16x16x32_bf16 v[122:125], v[166:169], v[194:197], v[122:125]
	v_mfma_f32_16x16x32_bf16 v[110:113], v[158:161], v[202:205], v[110:113]
	v_mfma_f32_16x16x32_bf16 v[106:109], v[166:169], v[202:205], v[106:109]
	v_mfma_f32_16x16x32_bf16 v[94:97], v[158:161], v[210:213], v[94:97]
	v_mfma_f32_16x16x32_bf16 v[90:93], v[166:169], v[210:213], v[90:93]
	v_mfma_f32_16x16x32_bf16 v[78:81], v[158:161], v[218:221], v[78:81]
	v_mfma_f32_16x16x32_bf16 v[74:77], v[166:169], v[218:221], v[74:77]
	s_setprio 0
	s_setprio 1
	v_mfma_f32_16x16x32_bf16 v[118:121], v[170:173], v[190:193], v[118:121]
	v_mfma_f32_16x16x32_bf16 v[114:117], v[182:185], v[190:193], v[114:117]
	v_mfma_f32_16x16x32_bf16 v[102:105], v[170:173], v[198:201], v[102:105]
	v_mfma_f32_16x16x32_bf16 v[98:101], v[182:185], v[198:201], v[98:101]
	v_mfma_f32_16x16x32_bf16 v[86:89], v[170:173], v[206:209], v[86:89]
	v_mfma_f32_16x16x32_bf16 v[82:85], v[182:185], v[206:209], v[82:85]
	v_mfma_f32_16x16x32_bf16 v[70:73], v[170:173], v[214:217], v[70:73]
	v_mfma_f32_16x16x32_bf16 v[66:69], v[182:185], v[214:217], v[66:69]
	v_mfma_f32_16x16x32_bf16 v[118:121], v[174:177], v[194:197], v[118:121]
	v_mfma_f32_16x16x32_bf16 v[114:117], v[186:189], v[194:197], v[114:117]
	v_mfma_f32_16x16x32_bf16 v[102:105], v[174:177], v[202:205], v[102:105]
	v_mfma_f32_16x16x32_bf16 v[98:101], v[186:189], v[202:205], v[98:101]
	v_mfma_f32_16x16x32_bf16 v[86:89], v[174:177], v[210:213], v[86:89]
	v_mfma_f32_16x16x32_bf16 v[82:85], v[186:189], v[210:213], v[82:85]
	v_mfma_f32_16x16x32_bf16 v[70:73], v[174:177], v[218:221], v[70:73]
	v_mfma_f32_16x16x32_bf16 v[66:69], v[186:189], v[218:221], v[66:69]
	s_setprio 0
	s_barrier
	s_add_i32 s72, s72, s44
	s_mov_b32 m0, s72
	ds_read_b128 v[190:193], v151 offset:16384
	ds_read_b128 v[194:197], v151 offset:17408
	ds_read_b128 v[198:201], v151 offset:18432
	ds_read_b128 v[202:205], v151 offset:19456
	ds_read_b128 v[206:209], v151 offset:20480
	ds_read_b128 v[210:213], v151 offset:21504
	ds_read_b128 v[214:217], v151 offset:22528
	ds_read_b128 v[218:221], v151 offset:23552
	global_load_lds_dwordx4 v132, s[6:7]
	s_add_i32 m0, s72, 0x2000
	s_add_u32 s100, s6, 0x80
	s_addc_u32 s101, s7, 0
	global_load_lds_dwordx4 v136, s[6:7]
	s_add_u32 s6, s6, s20
	s_addc_u32 s7, s7, s21
	s_add_i32 s33, s33, s44
	s_mov_b32 m0, s33
	s_nop 0
	global_load_lds_dwordx4 v132, s[6:7]
	s_add_i32 m0, s33, 0x2000
	s_nop 0
	global_load_lds_dwordx4 v136, s[6:7]
	s_mov_b32 m0, s45
	s_nop 0
	global_load_lds_dwordx4 v130, s[40:41]
	s_mov_b32 m0, s46
	s_nop 0
	global_load_lds_dwordx4 v134, s[40:41]
	s_waitcnt vmcnt(8)
	s_waitcnt lgkmcnt(0)
	s_barrier
	s_setprio 1
	s_waitcnt lgkmcnt(0)
	v_mfma_f32_16x16x32_bf16 v[62:65], v[144:147], v[190:193], v[62:65]
	v_mfma_f32_16x16x32_bf16 v[58:61], v[162:165], v[190:193], v[58:61]
	v_mfma_f32_16x16x32_bf16 v[46:49], v[144:147], v[198:201], v[46:49]
	v_mfma_f32_16x16x32_bf16 v[42:45], v[162:165], v[198:201], v[42:45]
	v_mfma_f32_16x16x32_bf16 v[30:33], v[144:147], v[206:209], v[30:33]
	v_mfma_f32_16x16x32_bf16 v[26:29], v[162:165], v[206:209], v[26:29]
	v_mfma_f32_16x16x32_bf16 v[14:17], v[144:147], v[214:217], v[14:17]
	v_mfma_f32_16x16x32_bf16 v[10:13], v[162:165], v[214:217], v[10:13]
	v_mfma_f32_16x16x32_bf16 v[62:65], v[158:161], v[194:197], v[62:65]
	v_mfma_f32_16x16x32_bf16 v[58:61], v[166:169], v[194:197], v[58:61]
	v_mfma_f32_16x16x32_bf16 v[46:49], v[158:161], v[202:205], v[46:49]
	v_mfma_f32_16x16x32_bf16 v[42:45], v[166:169], v[202:205], v[42:45]
	v_mfma_f32_16x16x32_bf16 v[30:33], v[158:161], v[210:213], v[30:33]
	v_mfma_f32_16x16x32_bf16 v[26:29], v[166:169], v[210:213], v[26:29]
	v_mfma_f32_16x16x32_bf16 v[14:17], v[158:161], v[218:221], v[14:17]
	v_mfma_f32_16x16x32_bf16 v[10:13], v[166:169], v[218:221], v[10:13]
	s_setprio 0
	s_setprio 1
	v_mfma_f32_16x16x32_bf16 v[54:57], v[170:173], v[190:193], v[54:57]
	v_mfma_f32_16x16x32_bf16 v[50:53], v[182:185], v[190:193], v[50:53]
	v_mfma_f32_16x16x32_bf16 v[38:41], v[170:173], v[198:201], v[38:41]
	v_mfma_f32_16x16x32_bf16 v[34:37], v[182:185], v[198:201], v[34:37]
	v_mfma_f32_16x16x32_bf16 v[22:25], v[170:173], v[206:209], v[22:25]
	v_mfma_f32_16x16x32_bf16 v[18:21], v[182:185], v[206:209], v[18:21]
	v_mfma_f32_16x16x32_bf16 v[6:9], v[170:173], v[214:217], v[6:9]
	v_mfma_f32_16x16x32_bf16 v[2:5], v[182:185], v[214:217], v[2:5]
	v_mfma_f32_16x16x32_bf16 v[54:57], v[174:177], v[194:197], v[54:57]
	v_mfma_f32_16x16x32_bf16 v[50:53], v[186:189], v[194:197], v[50:53]
	v_mfma_f32_16x16x32_bf16 v[38:41], v[174:177], v[202:205], v[38:41]
	v_mfma_f32_16x16x32_bf16 v[34:37], v[186:189], v[202:205], v[34:37]
	v_mfma_f32_16x16x32_bf16 v[22:25], v[174:177], v[210:213], v[22:25]
	v_mfma_f32_16x16x32_bf16 v[18:21], v[186:189], v[210:213], v[18:21]
	v_mfma_f32_16x16x32_bf16 v[6:9], v[174:177], v[218:221], v[6:9]
	v_mfma_f32_16x16x32_bf16 v[2:5], v[186:189], v[218:221], v[2:5]
	s_setprio 0
	s_barrier
; #define PG8_STAGE(bufoff, gbase, voff) do { _Pragma("unroll") for (int _i = 0; _i < 2; ++_i) \
;         __builtin_amdgcn_global_load_lds((const unsigned*)((const char*)(gbase) + (voff)[_i]), (PG8_LAS unsigned*)(lds + (bufoff) + ldsw + _i * 8192), 16, 0, 0); } while (0)
; #define PG8_LDA(dst, b, h) do { _Pragma("unroll") for (int m = 0; m < 4; ++m) _Pragma("unroll") for (int k = 0; k < 2; ++k) dst[m][k] = *(const PG8_LAS bf16x8*)(lds + PG8_SA(b, h) + aoff + m * 2048 + k * 1024); } while (0)
; #define PG8_LDB(dst, b, h) do { _Pragma("unroll") for (int n = 0; n < 2; ++n) _Pragma("unroll") for (int k = 0; k < 2; ++k) dst[n][k] = *(const PG8_LAS bf16x8*)(lds + PG8_SB(b, h) + boff + n * 2048 + k * 1024); } while (0)
; #define PG8_WAIT_V(n) asm volatile("s_waitcnt vmcnt(" #n ")" ::: "memory")
; #define PG8_WAIT_L(n) asm volatile("s_waitcnt lgkmcnt(" #n ")" ::: "memory")
; template <class Epi, class Sched, bool ALIGN_EPI = false, bool SP2 = false>
; __device__ __forceinline__ void gemm_phase(PG8_LAS unsigned char* lds, const Gemm g, const Sched& S, const Epi& E) {
;     ...
;             const char* a2 = last ? nA : cA + (size_t)(t + 2) * kstep; const char* b2 = last ? nB : cB + (size_t)(t + 2) * kstep;
;             const char* a3 = a2 + kstep; const char* b3 = b2 + kstep;
;             if (last && has_next) S.a_ready(nxt);
;             if constexpr (SP2) {
;             PG8_LDB(B0, 0, 0); PG8_LDB(B1, 0, 1); PG8_SCHED; PG8_LDA(At, 0, 0); PG8_STAGE(PG8_SA(1, 1), a1 + hstep, voffA);
;             PG8_WAIT_V(8); PG8_WAIT_L(0); PG8_BAR; PG8_MMA(0, 0, At, B0); PG8_MMA(0, 1, At, B1); PG8_BAR; PG8_SCHED;
;             PG8_LDA(At, 0, 1); PG8_STAGE(PG8_SB(0, 0), b2, voffB); PG8_STAGE(PG8_SB(0, 1), b2 + hstep, voffB); PG8_STAGE(PG8_SA(0, 0), a2, voffA);
;             PG8_WAIT_V(8); PG8_WAIT_L(0); PG8_BAR; PG8_MMA(1, 0, At, B0); PG8_MMA(1, 1, At, B1); PG8_BAR; PG8_SCHED;
;             PG8_LDB(B0, 1, 0); PG8_LDB(B1, 1, 1); PG8_SCHED; PG8_LDA(At, 1, 0); PG8_STAGE(PG8_SA(0, 1), a2 + hstep, voffA);
;             PG8_WAIT_V(8); PG8_WAIT_L(0); PG8_BAR; PG8_MMA(0, 0, At, B0); PG8_MMA(0, 1, At, B1); PG8_BAR; PG8_SCHED;
;             PG8_LDA(At, 1, 1); PG8_STAGE(PG8_SB(1, 0), b3, voffB); PG8_STAGE(PG8_SB(1, 1), b3 + hstep, voffB); PG8_STAGE(PG8_SA(1, 0), a3, voffA);
;             PG8_WAIT_V(8); PG8_WAIT_L(0); PG8_BAR; PG8_MMA(1, 0, At, B0); PG8_MMA(1, 1, At, B1); PG8_BAR; PG8_SCHED;
	s_add_i32 s33, 0, 0x18000
	s_add_i32 s72, 0, 0x1c000
	v_add_u32_e32 v166, s33, v148
	v_add_u32_e32 v181, s72, v148
	ds_read_b128 v[144:147], v166
	ds_read_b128 v[158:161], v166 offset:1024
	ds_read_b128 v[162:165], v166 offset:2048
	ds_read_b128 v[166:169], v166 offset:3072
	ds_read_b128 v[170:173], v181
	ds_read_b128 v[174:177], v181 offset:1024
	ds_read_b128 v[182:185], v181 offset:2048
	ds_read_b128 v[186:189], v181 offset:3072
	s_add_u32 s6, s40, s20
	s_addc_u32 s7, s41, s21
	s_mov_b32 m0, s47
	ds_read_b128 v[190:193], v151 offset:32768
	ds_read_b128 v[194:197], v151 offset:33792
	ds_read_b128 v[198:201], v151 offset:34816
	ds_read_b128 v[202:205], v151 offset:35840
	ds_read_b128 v[206:209], v151 offset:36864
	ds_read_b128 v[210:213], v151 offset:37888
	ds_read_b128 v[214:217], v151 offset:38912
	ds_read_b128 v[218:221], v151 offset:39936
	global_load_lds_dwordx4 v130, s[6:7]
	s_mov_b32 m0, s48
	s_nop 0
	global_load_lds_dwordx4 v134, s[6:7]
	s_waitcnt vmcnt(8)
	s_waitcnt lgkmcnt(0)
	s_barrier
	s_setprio 1
	s_waitcnt lgkmcnt(0)
	v_mfma_f32_16x16x32_bf16 v[126:129], v[144:147], v[190:193], v[126:129]
	v_mfma_f32_16x16x32_bf16 v[122:125], v[162:165], v[190:193], v[122:125]
	v_mfma_f32_16x16x32_bf16 v[110:113], v[144:147], v[198:201], v[110:113]
	v_mfma_f32_16x16x32_bf16 v[106:109], v[162:165], v[198:201], v[106:109]
	v_mfma_f32_16x16x32_bf16 v[94:97], v[144:147], v[206:209], v[94:97]
	v_mfma_f32_16x16x32_bf16 v[90:93], v[162:165], v[206:209], v[90:93]
	v_mfma_f32_16x16x32_bf16 v[78:81], v[144:147], v[214:217], v[78:81]
	v_mfma_f32_16x16x32_bf16 v[74:77], v[162:165], v[214:217], v[74:77]
	v_mfma_f32_16x16x32_bf16 v[126:129], v[158:161], v[194:197], v[126:129]
	v_mfma_f32_16x16x32_bf16 v[122:125], v[166:169], v[194:197], v[122:125]
	v_mfma_f32_16x16x32_bf16 v[110:113], v[158:161], v[202:205], v[110:113]
	v_mfma_f32_16x16x32_bf16 v[106:109], v[166:169], v[202:205], v[106:109]
	v_mfma_f32_16x16x32_bf16 v[94:97], v[158:161], v[210:213], v[94:97]
	v_mfma_f32_16x16x32_bf16 v[90:93], v[166:169], v[210:213], v[90:93]
	v_mfma_f32_16x16x32_bf16 v[78:81], v[158:161], v[218:221], v[78:81]
	v_mfma_f32_16x16x32_bf16 v[74:77], v[166:169], v[218:221], v[74:77]
	s_setprio 0
	s_setprio 1
	v_mfma_f32_16x16x32_bf16 v[118:121], v[170:173], v[190:193], v[118:121]
	v_mfma_f32_16x16x32_bf16 v[114:117], v[182:185], v[190:193], v[114:117]
	v_mfma_f32_16x16x32_bf16 v[102:105], v[170:173], v[198:201], v[102:105]
	v_mfma_f32_16x16x32_bf16 v[98:101], v[182:185], v[198:201], v[98:101]
	v_mfma_f32_16x16x32_bf16 v[86:89], v[170:173], v[206:209], v[86:89]
	v_mfma_f32_16x16x32_bf16 v[82:85], v[182:185], v[206:209], v[82:85]
	v_mfma_f32_16x16x32_bf16 v[70:73], v[170:173], v[214:217], v[70:73]
	v_mfma_f32_16x16x32_bf16 v[66:69], v[182:185], v[214:217], v[66:69]
	v_mfma_f32_16x16x32_bf16 v[118:121], v[174:177], v[194:197], v[118:121]
	v_mfma_f32_16x16x32_bf16 v[114:117], v[186:189], v[194:197], v[114:117]
	v_mfma_f32_16x16x32_bf16 v[102:105], v[174:177], v[202:205], v[102:105]
	v_mfma_f32_16x16x32_bf16 v[98:101], v[186:189], v[202:205], v[98:101]
	v_mfma_f32_16x16x32_bf16 v[86:89], v[174:177], v[210:213], v[86:89]
	v_mfma_f32_16x16x32_bf16 v[82:85], v[186:189], v[210:213], v[82:85]
	v_mfma_f32_16x16x32_bf16 v[70:73], v[174:177], v[218:221], v[70:73]
	v_mfma_f32_16x16x32_bf16 v[66:69], v[186:189], v[218:221], v[66:69]
	s_setprio 0
	s_barrier
	s_add_i32 s6, s33, s44
	s_mov_b32 m0, s6
	ds_read_b128 v[190:193], v151 offset:49152
	ds_read_b128 v[194:197], v151 offset:50176
	ds_read_b128 v[198:201], v151 offset:51200
	ds_read_b128 v[202:205], v151 offset:52224
	ds_read_b128 v[206:209], v151 offset:53248
	ds_read_b128 v[210:213], v151 offset:54272
	ds_read_b128 v[214:217], v151 offset:55296
	ds_read_b128 v[218:221], v151 offset:56320
	global_load_lds_dwordx4 v132, s[100:101]
	s_add_i32 m0, s6, 0x2000
	s_add_i32 s6, s72, s44
	global_load_lds_dwordx4 v136, s[100:101]
	s_add_u32 s100, s100, s20
	s_addc_u32 s101, s101, s21
	s_mov_b32 m0, s6
	s_nop 0
	global_load_lds_dwordx4 v132, s[100:101]
	s_add_i32 m0, s6, 0x2000
	s_nop 0
	global_load_lds_dwordx4 v136, s[100:101]
	s_add_u32 s100, s40, 0x80
	s_addc_u32 s101, s41, 0
	s_mov_b32 m0, s50
	s_nop 0
	global_load_lds_dwordx4 v130, s[100:101]
	s_mov_b32 m0, s51
	s_nop 0
	global_load_lds_dwordx4 v134, s[100:101]
	s_waitcnt vmcnt(8)
	s_waitcnt lgkmcnt(0)
	s_barrier
	s_setprio 1
	s_waitcnt lgkmcnt(0)
	v_mfma_f32_16x16x32_bf16 v[62:65], v[144:147], v[190:193], v[62:65]
	v_mfma_f32_16x16x32_bf16 v[58:61], v[162:165], v[190:193], v[58:61]
	v_mfma_f32_16x16x32_bf16 v[46:49], v[144:147], v[198:201], v[46:49]
	v_mfma_f32_16x16x32_bf16 v[42:45], v[162:165], v[198:201], v[42:45]
	v_mfma_f32_16x16x32_bf16 v[30:33], v[144:147], v[206:209], v[30:33]
	v_mfma_f32_16x16x32_bf16 v[26:29], v[162:165], v[206:209], v[26:29]
	v_mfma_f32_16x16x32_bf16 v[14:17], v[144:147], v[214:217], v[14:17]
	v_mfma_f32_16x16x32_bf16 v[10:13], v[162:165], v[214:217], v[10:13]
	v_mfma_f32_16x16x32_bf16 v[62:65], v[158:161], v[194:197], v[62:65]
	v_mfma_f32_16x16x32_bf16 v[58:61], v[166:169], v[194:197], v[58:61]
	v_mfma_f32_16x16x32_bf16 v[46:49], v[158:161], v[202:205], v[46:49]
	v_mfma_f32_16x16x32_bf16 v[42:45], v[166:169], v[202:205], v[42:45]
	v_mfma_f32_16x16x32_bf16 v[30:33], v[158:161], v[210:213], v[30:33]
	v_mfma_f32_16x16x32_bf16 v[26:29], v[166:169], v[210:213], v[26:29]
	v_mfma_f32_16x16x32_bf16 v[14:17], v[158:161], v[218:221], v[14:17]
	v_mfma_f32_16x16x32_bf16 v[10:13], v[166:169], v[218:221], v[10:13]
	s_setprio 0
	s_setprio 1
	v_mfma_f32_16x16x32_bf16 v[54:57], v[170:173], v[190:193], v[54:57]
	v_mfma_f32_16x16x32_bf16 v[50:53], v[182:185], v[190:193], v[50:53]
	v_mfma_f32_16x16x32_bf16 v[38:41], v[170:173], v[198:201], v[38:41]
	v_mfma_f32_16x16x32_bf16 v[34:37], v[182:185], v[198:201], v[34:37]
	v_mfma_f32_16x16x32_bf16 v[22:25], v[170:173], v[206:209], v[22:25]
	v_mfma_f32_16x16x32_bf16 v[18:21], v[182:185], v[206:209], v[18:21]
	v_mfma_f32_16x16x32_bf16 v[6:9], v[170:173], v[214:217], v[6:9]
	v_mfma_f32_16x16x32_bf16 v[2:5], v[182:185], v[214:217], v[2:5]
	v_mfma_f32_16x16x32_bf16 v[54:57], v[174:177], v[194:197], v[54:57]
	v_mfma_f32_16x16x32_bf16 v[50:53], v[186:189], v[194:197], v[50:53]
	v_mfma_f32_16x16x32_bf16 v[38:41], v[174:177], v[202:205], v[38:41]
	v_mfma_f32_16x16x32_bf16 v[34:37], v[186:189], v[202:205], v[34:37]
	v_mfma_f32_16x16x32_bf16 v[22:25], v[174:177], v[210:213], v[22:25]
	v_mfma_f32_16x16x32_bf16 v[18:21], v[186:189], v[210:213], v[18:21]
	v_mfma_f32_16x16x32_bf16 v[6:9], v[174:177], v[218:221], v[6:9]
	v_mfma_f32_16x16x32_bf16 v[2:5], v[186:189], v[218:221], v[2:5]
	s_setprio 0
	s_barrier
	s_add_u32 s38, s38, 0x100
	s_addc_u32 s39, s39, 0
	s_add_u32 s79, s79, 0x100
	s_addc_u32 s80, s80, 0
	s_cmp_ge_i32 s59, s49
	s_mov_b32 s33, s59
	s_cbranch_scc0 .LBB0_300

; #define PG8_STAGE(bufoff, gbase, voff) do { _Pragma("unroll") for (int _i = 0; _i < 2; ++_i) \
;         __builtin_amdgcn_global_load_lds((const unsigned*)((const char*)(gbase) + (voff)[_i]), (PG8_LAS unsigned*)(lds + (bufoff) + ldsw + _i * 8192), 16, 0, 0); } while (0)
; #define PG8_LDA(dst, b, h) do { _Pragma("unroll") for (int m = 0; m < 4; ++m) _Pragma("unroll") for (int k = 0; k < 2; ++k) dst[m][k] = *(const PG8_LAS bf16x8*)(lds + PG8_SA(b, h) + aoff + m * 2048 + k * 1024); } while (0)
; #define PG8_LDB(dst, b, h) do { _Pragma("unroll") for (int n = 0; n < 2; ++n) _Pragma("unroll") for (int k = 0; k < 2; ++k) dst[n][k] = *(const PG8_LAS bf16x8*)(lds + PG8_SB(b, h) + boff + n * 2048 + k * 1024); } while (0)
; #define PG8_MMA(ai, bj, At, Bt) do { __builtin_amdgcn_s_setprio(1); _Pragma("unroll") for (int m = 0; m < 4; ++m) _Pragma("unroll") for (int n = 0; n < 2; ++n) _Pragma("unroll") for (int k = 0; k < 2; ++k) \
;         acc[ai][bj][m][n] = __builtin_amdgcn_mfma_f32_16x16x32_bf16(Bt[n][k], At[m][k], acc[ai][bj][m][n], 0, 0, 0); __builtin_amdgcn_s_setprio(0); } while (0)
; #define PG8_WAIT_V(n) asm volatile("s_waitcnt vmcnt(" #n ")" ::: "memory")
; #define PG8_BAR __builtin_amdgcn_s_barrier()
; template <class Epi, class Sched, bool ALIGN_EPI = false, bool SP2 = false>
; __device__ __forceinline__ void gemm_phase(PG8_LAS unsigned char* lds, const Gemm g, const Sched& S, const Epi& E) {
;     ...
;         for (int t = 0; t < nt; t += 2) {
;             const bool last = (t == nt - 2);
;             const char* a1 = cA + (size_t)(t + 1) * kstep;
;             const char* a2 = last ? nA : cA + (size_t)(t + 2) * kstep; const char* b2 = last ? nB : cB + (size_t)(t + 2) * kstep;
;             const char* a3 = a2 + kstep; const char* b3 = b2 + kstep;
;             if (last && has_next) S.a_ready(nxt);
;             if constexpr (SP2) {
;             PG8_LDB(B0, 0, 0); PG8_LDB(B1, 0, 1); PG8_SCHED; PG8_LDA(At, 0, 0); PG8_STAGE(PG8_SA(1, 1), a1 + hstep, voffA);
;             PG8_WAIT_V(8); PG8_WAIT_L(0); PG8_BAR; PG8_MMA(0, 0, At, B0); PG8_MMA(0, 1, At, B1); PG8_BAR; PG8_SCHED;
;             PG8_LDA(At, 0, 1); PG8_STAGE(PG8_SB(0, 0), b2, voffB); PG8_STAGE(PG8_SB(0, 1), b2 + hstep, voffB); PG8_STAGE(PG8_SA(0, 0), a2, voffA);
;             PG8_WAIT_V(8); PG8_WAIT_L(0); PG8_BAR; PG8_MMA(1, 0, At, B0); PG8_MMA(1, 1, At, B1); PG8_BAR; PG8_SCHED;
.LBB0_406:
	s_add_i32 s59, s33, 2
	s_add_u32 s6, s34, 0x80
	s_addc_u32 s7, s35, 0
	s_add_i32 s72, 0, 0x10000
	s_cmp_eq_u32 s56, s33
	s_cselect_b32 s37, s11, s7
	s_cselect_b32 s36, s10, s6
	v_add_u32_e32 v148, s72, v150
	s_cselect_b32 s7, s31, s79
	s_cselect_b32 s6, s30, s67
	s_add_i32 s33, 0, 0x14000
	ds_read_b128 v[144:147], v148
	ds_read_b128 v[160:163], v148 offset:1024
	ds_read_b128 v[164:167], v148 offset:2048
	ds_read_b128 v[168:171], v148 offset:3072
	v_add_u32_e32 v148, s33, v150
	ds_read_b128 v[172:175], v148
	ds_read_b128 v[176:179], v148 offset:1024
	ds_read_b128 v[182:185], v148 offset:2048
	ds_read_b128 v[186:189], v148 offset:3072
	s_add_i32 m0, s46, 0xc000
	ds_read_b128 v[190:193], v158
	ds_read_b128 v[194:197], v158 offset:1024
	ds_read_b128 v[198:201], v158 offset:2048
	ds_read_b128 v[202:205], v158 offset:3072
	ds_read_b128 v[206:209], v158 offset:4096
	ds_read_b128 v[210:213], v158 offset:5120
	ds_read_b128 v[214:217], v158 offset:6144
	ds_read_b128 v[218:221], v158 offset:7168
	global_load_lds_dwordx4 v140, s[34:35]
	s_add_i32 m0, s46, 0xe000
	s_nop 0
	global_load_lds_dwordx4 v142, s[34:35]
	s_waitcnt vmcnt(8)
	s_waitcnt lgkmcnt(0)
	s_barrier
	s_setprio 1
	s_waitcnt lgkmcnt(0)
	v_mfma_f32_16x16x32_bf16 v[122:125], v[144:147], v[190:193], v[122:125]
	v_mfma_f32_16x16x32_bf16 v[126:129], v[164:167], v[190:193], v[126:129]
	v_mfma_f32_16x16x32_bf16 v[110:113], v[144:147], v[198:201], v[110:113]
	v_mfma_f32_16x16x32_bf16 v[106:109], v[164:167], v[198:201], v[106:109]
	v_mfma_f32_16x16x32_bf16 v[94:97], v[144:147], v[206:209], v[94:97]
	v_mfma_f32_16x16x32_bf16 v[90:93], v[164:167], v[206:209], v[90:93]
	v_mfma_f32_16x16x32_bf16 v[78:81], v[144:147], v[214:217], v[78:81]
	v_mfma_f32_16x16x32_bf16 v[74:77], v[164:167], v[214:217], v[74:77]
	v_mfma_f32_16x16x32_bf16 v[122:125], v[160:163], v[194:197], v[122:125]
	v_mfma_f32_16x16x32_bf16 v[126:129], v[168:171], v[194:197], v[126:129]
	v_mfma_f32_16x16x32_bf16 v[110:113], v[160:163], v[202:205], v[110:113]
	v_mfma_f32_16x16x32_bf16 v[106:109], v[168:171], v[202:205], v[106:109]
	v_mfma_f32_16x16x32_bf16 v[94:97], v[160:163], v[210:213], v[94:97]
	v_mfma_f32_16x16x32_bf16 v[90:93], v[168:171], v[210:213], v[90:93]
	v_mfma_f32_16x16x32_bf16 v[78:81], v[160:163], v[218:221], v[78:81]
	v_mfma_f32_16x16x32_bf16 v[74:77], v[168:171], v[218:221], v[74:77]
	s_setprio 0
	s_setprio 1
	v_mfma_f32_16x16x32_bf16 v[118:121], v[172:175], v[190:193], v[118:121]
	v_mfma_f32_16x16x32_bf16 v[114:117], v[182:185], v[190:193], v[114:117]
	v_mfma_f32_16x16x32_bf16 v[102:105], v[172:175], v[198:201], v[102:105]
	v_mfma_f32_16x16x32_bf16 v[98:101], v[182:185], v[198:201], v[98:101]
	v_mfma_f32_16x16x32_bf16 v[86:89], v[172:175], v[206:209], v[86:89]
	v_mfma_f32_16x16x32_bf16 v[82:85], v[182:185], v[206:209], v[82:85]
	v_mfma_f32_16x16x32_bf16 v[70:73], v[172:175], v[214:217], v[70:73]
	v_mfma_f32_16x16x32_bf16 v[66:69], v[182:185], v[214:217], v[66:69]
	v_mfma_f32_16x16x32_bf16 v[118:121], v[176:179], v[194:197], v[118:121]
	v_mfma_f32_16x16x32_bf16 v[114:117], v[186:189], v[194:197], v[114:117]
	v_mfma_f32_16x16x32_bf16 v[102:105], v[176:179], v[202:205], v[102:105]
	v_mfma_f32_16x16x32_bf16 v[98:101], v[186:189], v[202:205], v[98:101]
	v_mfma_f32_16x16x32_bf16 v[86:89], v[176:179], v[210:213], v[86:89]
	v_mfma_f32_16x16x32_bf16 v[82:85], v[186:189], v[210:213], v[82:85]
	v_mfma_f32_16x16x32_bf16 v[70:73], v[176:179], v[218:221], v[70:73]
	v_mfma_f32_16x16x32_bf16 v[66:69], v[186:189], v[218:221], v[66:69]
	s_setprio 0
	s_barrier
	s_add_i32 s72, s72, s40
	s_mov_b32 m0, s72
	ds_read_b128 v[190:193], v158 offset:16384
	ds_read_b128 v[194:197], v158 offset:17408
	ds_read_b128 v[198:201], v158 offset:18432
	ds_read_b128 v[202:205], v158 offset:19456
	ds_read_b128 v[206:209], v158 offset:20480
	ds_read_b128 v[210:213], v158 offset:21504
	ds_read_b128 v[214:217], v158 offset:22528
	ds_read_b128 v[218:221], v158 offset:23552
	global_load_lds_dwordx4 v134, s[6:7]
	s_add_i32 m0, s72, 0x2000
	s_add_u32 s100, s6, 0x80
	s_addc_u32 s101, s7, 0
	global_load_lds_dwordx4 v130, s[6:7]
	s_add_u32 s6, s6, s16
	s_addc_u32 s7, s7, s17
	s_add_i32 s33, s33, s40
	s_mov_b32 m0, s33
	s_nop 0
	global_load_lds_dwordx4 v134, s[6:7]
	s_add_i32 m0, s33, 0x2000
	s_nop 0
	global_load_lds_dwordx4 v130, s[6:7]
	s_mov_b32 m0, s46
	s_nop 0
	global_load_lds_dwordx4 v136, s[36:37]
	s_mov_b32 m0, s47
	s_nop 0
	global_load_lds_dwordx4 v132, s[36:37]
	s_waitcnt vmcnt(8)
	s_waitcnt lgkmcnt(0)
	s_barrier
	s_setprio 1
	s_waitcnt lgkmcnt(0)
	v_mfma_f32_16x16x32_bf16 v[62:65], v[144:147], v[190:193], v[62:65]
	v_mfma_f32_16x16x32_bf16 v[58:61], v[164:167], v[190:193], v[58:61]
	v_mfma_f32_16x16x32_bf16 v[46:49], v[144:147], v[198:201], v[46:49]
	v_mfma_f32_16x16x32_bf16 v[42:45], v[164:167], v[198:201], v[42:45]
	v_mfma_f32_16x16x32_bf16 v[30:33], v[144:147], v[206:209], v[30:33]
	v_mfma_f32_16x16x32_bf16 v[26:29], v[164:167], v[206:209], v[26:29]
	v_mfma_f32_16x16x32_bf16 v[14:17], v[144:147], v[214:217], v[14:17]
	v_mfma_f32_16x16x32_bf16 v[10:13], v[164:167], v[214:217], v[10:13]
	v_mfma_f32_16x16x32_bf16 v[62:65], v[160:163], v[194:197], v[62:65]
	v_mfma_f32_16x16x32_bf16 v[58:61], v[168:171], v[194:197], v[58:61]
	v_mfma_f32_16x16x32_bf16 v[46:49], v[160:163], v[202:205], v[46:49]
	v_mfma_f32_16x16x32_bf16 v[42:45], v[168:171], v[202:205], v[42:45]
	v_mfma_f32_16x16x32_bf16 v[30:33], v[160:163], v[210:213], v[30:33]
	v_mfma_f32_16x16x32_bf16 v[26:29], v[168:171], v[210:213], v[26:29]
	v_mfma_f32_16x16x32_bf16 v[14:17], v[160:163], v[218:221], v[14:17]
	v_mfma_f32_16x16x32_bf16 v[10:13], v[168:171], v[218:221], v[10:13]
	s_setprio 0
	s_setprio 1
	v_mfma_f32_16x16x32_bf16 v[54:57], v[172:175], v[190:193], v[54:57]
	v_mfma_f32_16x16x32_bf16 v[50:53], v[182:185], v[190:193], v[50:53]
	v_mfma_f32_16x16x32_bf16 v[38:41], v[172:175], v[198:201], v[38:41]
	v_mfma_f32_16x16x32_bf16 v[34:37], v[182:185], v[198:201], v[34:37]
	v_mfma_f32_16x16x32_bf16 v[22:25], v[172:175], v[206:209], v[22:25]
	v_mfma_f32_16x16x32_bf16 v[18:21], v[182:185], v[206:209], v[18:21]
	v_mfma_f32_16x16x32_bf16 v[6:9], v[172:175], v[214:217], v[6:9]
	v_mfma_f32_16x16x32_bf16 v[2:5], v[182:185], v[214:217], v[2:5]
	v_mfma_f32_16x16x32_bf16 v[54:57], v[176:179], v[194:197], v[54:57]
	v_mfma_f32_16x16x32_bf16 v[50:53], v[186:189], v[194:197], v[50:53]
	v_mfma_f32_16x16x32_bf16 v[38:41], v[176:179], v[202:205], v[38:41]
	v_mfma_f32_16x16x32_bf16 v[34:37], v[186:189], v[202:205], v[34:37]
	v_mfma_f32_16x16x32_bf16 v[22:25], v[176:179], v[210:213], v[22:25]
	v_mfma_f32_16x16x32_bf16 v[18:21], v[186:189], v[210:213], v[18:21]
	v_mfma_f32_16x16x32_bf16 v[6:9], v[176:179], v[218:221], v[6:9]
	v_mfma_f32_16x16x32_bf16 v[2:5], v[186:189], v[218:221], v[2:5]
	s_setprio 0
	s_barrier
; #define PG8_STAGE(bufoff, gbase, voff) do { _Pragma("unroll") for (int _i = 0; _i < 2; ++_i) \
;         __builtin_amdgcn_global_load_lds((const unsigned*)((const char*)(gbase) + (voff)[_i]), (PG8_LAS unsigned*)(lds + (bufoff) + ldsw + _i * 8192), 16, 0, 0); } while (0)
; #define PG8_LDA(dst, b, h) do { _Pragma("unroll") for (int m = 0; m < 4; ++m) _Pragma("unroll") for (int k = 0; k < 2; ++k) dst[m][k] = *(const PG8_LAS bf16x8*)(lds + PG8_SA(b, h) + aoff + m * 2048 + k * 1024); } while (0)
; #define PG8_LDB(dst, b, h) do { _Pragma("unroll") for (int n = 0; n < 2; ++n) _Pragma("unroll") for (int k = 0; k < 2; ++k) dst[n][k] = *(const PG8_LAS bf16x8*)(lds + PG8_SB(b, h) + boff + n * 2048 + k * 1024); } while (0)
; #define PG8_WAIT_V(n) asm volatile("s_waitcnt vmcnt(" #n ")" ::: "memory")
; #define PG8_WAIT_L(n) asm volatile("s_waitcnt lgkmcnt(" #n ")" ::: "memory")
; template <class Epi, class Sched, bool ALIGN_EPI = false, bool SP2 = false>
; __device__ __forceinline__ void gemm_phase(PG8_LAS unsigned char* lds, const Gemm g, const Sched& S, const Epi& E) {
;     ...
;             const char* a2 = last ? nA : cA + (size_t)(t + 2) * kstep; const char* b2 = last ? nB : cB + (size_t)(t + 2) * kstep;
;             const char* a3 = a2 + kstep; const char* b3 = b2 + kstep;
;             if (last && has_next) S.a_ready(nxt);
;             if constexpr (SP2) {
;             PG8_LDB(B0, 0, 0); PG8_LDB(B1, 0, 1); PG8_SCHED; PG8_LDA(At, 0, 0); PG8_STAGE(PG8_SA(1, 1), a1 + hstep, voffA);
;             PG8_WAIT_V(8); PG8_WAIT_L(0); PG8_BAR; PG8_MMA(0, 0, At, B0); PG8_MMA(0, 1, At, B1); PG8_BAR; PG8_SCHED;
;             PG8_LDA(At, 0, 1); PG8_STAGE(PG8_SB(0, 0), b2, voffB); PG8_STAGE(PG8_SB(0, 1), b2 + hstep, voffB); PG8_STAGE(PG8_SA(0, 0), a2, voffA);
;             PG8_WAIT_V(8); PG8_WAIT_L(0); PG8_BAR; PG8_MMA(1, 0, At, B0); PG8_MMA(1, 1, At, B1); PG8_BAR; PG8_SCHED;
;             PG8_LDB(B0, 1, 0); PG8_LDB(B1, 1, 1); PG8_SCHED; PG8_LDA(At, 1, 0); PG8_STAGE(PG8_SA(0, 1), a2 + hstep, voffA);
;             PG8_WAIT_V(8); PG8_WAIT_L(0); PG8_BAR; PG8_MMA(0, 0, At, B0); PG8_MMA(0, 1, At, B1); PG8_BAR; PG8_SCHED;
;             PG8_LDA(At, 1, 1); PG8_STAGE(PG8_SB(1, 0), b3, voffB); PG8_STAGE(PG8_SB(1, 1), b3 + hstep, voffB); PG8_STAGE(PG8_SA(1, 0), a3, voffA);
;             PG8_WAIT_V(8); PG8_WAIT_L(0); PG8_BAR; PG8_MMA(1, 0, At, B0); PG8_MMA(1, 1, At, B1); PG8_BAR; PG8_SCHED;
	s_add_i32 s33, 0, 0x18000
	v_add_u32_e32 v159, s33, v150
	s_add_i32 s72, 0, 0x1c000
	ds_read_b128 v[144:147], v159
	ds_read_b128 v[160:163], v159 offset:1024
	ds_read_b128 v[164:167], v159 offset:2048
	ds_read_b128 v[168:171], v159 offset:3072
	v_add_u32_e32 v159, s72, v150
	ds_read_b128 v[172:175], v159
	ds_read_b128 v[176:179], v159 offset:1024
	ds_read_b128 v[182:185], v159 offset:2048
	ds_read_b128 v[186:189], v159 offset:3072
	s_add_u32 s6, s36, s16
	s_addc_u32 s7, s37, s17
	s_mov_b32 m0, s48
	ds_read_b128 v[190:193], v158 offset:32768
	ds_read_b128 v[194:197], v158 offset:33792
	ds_read_b128 v[198:201], v158 offset:34816
	ds_read_b128 v[202:205], v158 offset:35840
	ds_read_b128 v[206:209], v158 offset:36864
	ds_read_b128 v[210:213], v158 offset:37888
	ds_read_b128 v[214:217], v158 offset:38912
	ds_read_b128 v[218:221], v158 offset:39936
	global_load_lds_dwordx4 v136, s[6:7]
	s_mov_b32 m0, s49
	s_nop 0
	global_load_lds_dwordx4 v132, s[6:7]
	s_waitcnt vmcnt(8)
	s_waitcnt lgkmcnt(0)
	s_barrier
	s_setprio 1
	s_waitcnt lgkmcnt(0)
	v_mfma_f32_16x16x32_bf16 v[122:125], v[144:147], v[190:193], v[122:125]
	v_mfma_f32_16x16x32_bf16 v[126:129], v[164:167], v[190:193], v[126:129]
	v_mfma_f32_16x16x32_bf16 v[110:113], v[144:147], v[198:201], v[110:113]
	v_mfma_f32_16x16x32_bf16 v[106:109], v[164:167], v[198:201], v[106:109]
	v_mfma_f32_16x16x32_bf16 v[94:97], v[144:147], v[206:209], v[94:97]
	v_mfma_f32_16x16x32_bf16 v[90:93], v[164:167], v[206:209], v[90:93]
	v_mfma_f32_16x16x32_bf16 v[78:81], v[144:147], v[214:217], v[78:81]
	v_mfma_f32_16x16x32_bf16 v[74:77], v[164:167], v[214:217], v[74:77]
	v_mfma_f32_16x16x32_bf16 v[122:125], v[160:163], v[194:197], v[122:125]
	v_mfma_f32_16x16x32_bf16 v[126:129], v[168:171], v[194:197], v[126:129]
	v_mfma_f32_16x16x32_bf16 v[110:113], v[160:163], v[202:205], v[110:113]
	v_mfma_f32_16x16x32_bf16 v[106:109], v[168:171], v[202:205], v[106:109]
	v_mfma_f32_16x16x32_bf16 v[94:97], v[160:163], v[210:213], v[94:97]
	v_mfma_f32_16x16x32_bf16 v[90:93], v[168:171], v[210:213], v[90:93]
	v_mfma_f32_16x16x32_bf16 v[78:81], v[160:163], v[218:221], v[78:81]
	v_mfma_f32_16x16x32_bf16 v[74:77], v[168:171], v[218:221], v[74:77]
	s_setprio 0
	s_setprio 1
	v_mfma_f32_16x16x32_bf16 v[118:121], v[172:175], v[190:193], v[118:121]
	v_mfma_f32_16x16x32_bf16 v[114:117], v[182:185], v[190:193], v[114:117]
	v_mfma_f32_16x16x32_bf16 v[102:105], v[172:175], v[198:201], v[102:105]
	v_mfma_f32_16x16x32_bf16 v[98:101], v[182:185], v[198:201], v[98:101]
	v_mfma_f32_16x16x32_bf16 v[86:89], v[172:175], v[206:209], v[86:89]
	v_mfma_f32_16x16x32_bf16 v[82:85], v[182:185], v[206:209], v[82:85]
	v_mfma_f32_16x16x32_bf16 v[70:73], v[172:175], v[214:217], v[70:73]
	v_mfma_f32_16x16x32_bf16 v[66:69], v[182:185], v[214:217], v[66:69]
	v_mfma_f32_16x16x32_bf16 v[118:121], v[176:179], v[194:197], v[118:121]
	v_mfma_f32_16x16x32_bf16 v[114:117], v[186:189], v[194:197], v[114:117]
	v_mfma_f32_16x16x32_bf16 v[102:105], v[176:179], v[202:205], v[102:105]
	v_mfma_f32_16x16x32_bf16 v[98:101], v[186:189], v[202:205], v[98:101]
	v_mfma_f32_16x16x32_bf16 v[86:89], v[176:179], v[210:213], v[86:89]
	v_mfma_f32_16x16x32_bf16 v[82:85], v[186:189], v[210:213], v[82:85]
	v_mfma_f32_16x16x32_bf16 v[70:73], v[176:179], v[218:221], v[70:73]
	v_mfma_f32_16x16x32_bf16 v[66:69], v[186:189], v[218:221], v[66:69]
	s_setprio 0
	s_barrier
	s_add_i32 s6, s33, s40
	s_mov_b32 m0, s6
	ds_read_b128 v[190:193], v158 offset:49152
	ds_read_b128 v[194:197], v158 offset:50176
	ds_read_b128 v[198:201], v158 offset:51200
	ds_read_b128 v[202:205], v158 offset:52224
	ds_read_b128 v[206:209], v158 offset:53248
	ds_read_b128 v[210:213], v158 offset:54272
	ds_read_b128 v[214:217], v158 offset:55296
	ds_read_b128 v[218:221], v158 offset:56320
	global_load_lds_dwordx4 v134, s[100:101]
	s_add_i32 m0, s6, 0x2000
	s_add_i32 s6, s72, s40
	global_load_lds_dwordx4 v130, s[100:101]
	s_add_u32 s100, s100, s16
	s_addc_u32 s101, s101, s17
	s_mov_b32 m0, s6
	s_nop 0
	global_load_lds_dwordx4 v134, s[100:101]
	s_add_i32 m0, s6, 0x2000
	s_nop 0
	global_load_lds_dwordx4 v130, s[100:101]
	s_add_u32 s100, s36, 0x80
	s_addc_u32 s101, s37, 0
	s_mov_b32 m0, s51
	s_nop 0
	global_load_lds_dwordx4 v136, s[100:101]
	s_mov_b32 m0, s54
	s_nop 0
	global_load_lds_dwordx4 v132, s[100:101]
	s_waitcnt vmcnt(8)
	s_waitcnt lgkmcnt(0)
	s_barrier
	s_setprio 1
	s_waitcnt lgkmcnt(0)
	v_mfma_f32_16x16x32_bf16 v[62:65], v[144:147], v[190:193], v[62:65]
	v_mfma_f32_16x16x32_bf16 v[58:61], v[164:167], v[190:193], v[58:61]
	v_mfma_f32_16x16x32_bf16 v[46:49], v[144:147], v[198:201], v[46:49]
	v_mfma_f32_16x16x32_bf16 v[42:45], v[164:167], v[198:201], v[42:45]
	v_mfma_f32_16x16x32_bf16 v[30:33], v[144:147], v[206:209], v[30:33]
	v_mfma_f32_16x16x32_bf16 v[26:29], v[164:167], v[206:209], v[26:29]
	v_mfma_f32_16x16x32_bf16 v[14:17], v[144:147], v[214:217], v[14:17]
	v_mfma_f32_16x16x32_bf16 v[10:13], v[164:167], v[214:217], v[10:13]
	v_mfma_f32_16x16x32_bf16 v[62:65], v[160:163], v[194:197], v[62:65]
	v_mfma_f32_16x16x32_bf16 v[58:61], v[168:171], v[194:197], v[58:61]
	v_mfma_f32_16x16x32_bf16 v[46:49], v[160:163], v[202:205], v[46:49]
	v_mfma_f32_16x16x32_bf16 v[42:45], v[168:171], v[202:205], v[42:45]
	v_mfma_f32_16x16x32_bf16 v[30:33], v[160:163], v[210:213], v[30:33]
	v_mfma_f32_16x16x32_bf16 v[26:29], v[168:171], v[210:213], v[26:29]
	v_mfma_f32_16x16x32_bf16 v[14:17], v[160:163], v[218:221], v[14:17]
	v_mfma_f32_16x16x32_bf16 v[10:13], v[168:171], v[218:221], v[10:13]
	s_setprio 0
	s_setprio 1
	v_mfma_f32_16x16x32_bf16 v[54:57], v[172:175], v[190:193], v[54:57]
	v_mfma_f32_16x16x32_bf16 v[50:53], v[182:185], v[190:193], v[50:53]
	v_mfma_f32_16x16x32_bf16 v[38:41], v[172:175], v[198:201], v[38:41]
	v_mfma_f32_16x16x32_bf16 v[34:37], v[182:185], v[198:201], v[34:37]
	v_mfma_f32_16x16x32_bf16 v[22:25], v[172:175], v[206:209], v[22:25]
	v_mfma_f32_16x16x32_bf16 v[18:21], v[182:185], v[206:209], v[18:21]
	v_mfma_f32_16x16x32_bf16 v[6:9], v[172:175], v[214:217], v[6:9]
	v_mfma_f32_16x16x32_bf16 v[2:5], v[182:185], v[214:217], v[2:5]
	v_mfma_f32_16x16x32_bf16 v[54:57], v[176:179], v[194:197], v[54:57]
	v_mfma_f32_16x16x32_bf16 v[50:53], v[186:189], v[194:197], v[50:53]
	v_mfma_f32_16x16x32_bf16 v[38:41], v[176:179], v[202:205], v[38:41]
	v_mfma_f32_16x16x32_bf16 v[34:37], v[186:189], v[202:205], v[34:37]
	v_mfma_f32_16x16x32_bf16 v[22:25], v[176:179], v[210:213], v[22:25]
	v_mfma_f32_16x16x32_bf16 v[18:21], v[186:189], v[210:213], v[18:21]
	v_mfma_f32_16x16x32_bf16 v[6:9], v[176:179], v[218:221], v[6:9]
	v_mfma_f32_16x16x32_bf16 v[2:5], v[186:189], v[218:221], v[2:5]
	s_setprio 0
	s_barrier
	s_add_u32 s34, s34, 0x100
	s_addc_u32 s35, s35, 0
	s_add_u32 s67, s67, 0x100
	s_addc_u32 s79, s79, 0
	s_cmp_ge_i32 s59, s50
	s_mov_b32 s33, s59
	s_cbranch_scc0 .LBB0_406

; #define PG8_STAGE(bufoff, gbase, voff) do { _Pragma("unroll") for (int _i = 0; _i < 2; ++_i) \
;         __builtin_amdgcn_global_load_lds((const unsigned*)((const char*)(gbase) + (voff)[_i]), (PG8_LAS unsigned*)(lds + (bufoff) + ldsw + _i * 8192), 16, 0, 0); } while (0)
; #define PG8_LDA(dst, b, h) do { _Pragma("unroll") for (int m = 0; m < 4; ++m) _Pragma("unroll") for (int k = 0; k < 2; ++k) dst[m][k] = *(const PG8_LAS bf16x8*)(lds + PG8_SA(b, h) + aoff + m * 2048 + k * 1024); } while (0)
; #define PG8_LDB(dst, b, h) do { _Pragma("unroll") for (int n = 0; n < 2; ++n) _Pragma("unroll") for (int k = 0; k < 2; ++k) dst[n][k] = *(const PG8_LAS bf16x8*)(lds + PG8_SB(b, h) + boff + n * 2048 + k * 1024); } while (0)
; #define PG8_MMA(ai, bj, At, Bt) do { __builtin_amdgcn_s_setprio(1); _Pragma("unroll") for (int m = 0; m < 4; ++m) _Pragma("unroll") for (int n = 0; n < 2; ++n) _Pragma("unroll") for (int k = 0; k < 2; ++k) \
;         acc[ai][bj][m][n] = __builtin_amdgcn_mfma_f32_16x16x32_bf16(Bt[n][k], At[m][k], acc[ai][bj][m][n], 0, 0, 0); __builtin_amdgcn_s_setprio(0); } while (0)
; #define PG8_WAIT_V(n) asm volatile("s_waitcnt vmcnt(" #n ")" ::: "memory")
; #define PG8_BAR __builtin_amdgcn_s_barrier()
; template <class Epi, class Sched, bool ALIGN_EPI = false, bool SP2 = false>
; __device__ __forceinline__ void gemm_phase(PG8_LAS unsigned char* lds, const Gemm g, const Sched& S, const Epi& E) {
;     ...
;         for (int t = 0; t < nt; t += 2) {
;             const bool last = (t == nt - 2);
;             const char* a1 = cA + (size_t)(t + 1) * kstep;
;             const char* a2 = last ? nA : cA + (size_t)(t + 2) * kstep; const char* b2 = last ? nB : cB + (size_t)(t + 2) * kstep;
;             const char* a3 = a2 + kstep; const char* b3 = b2 + kstep;
;             if (last && has_next) S.a_ready(nxt);
;             if constexpr (SP2) {
;             PG8_LDB(B0, 0, 0); PG8_LDB(B1, 0, 1); PG8_SCHED; PG8_LDA(At, 0, 0); PG8_STAGE(PG8_SA(1, 1), a1 + hstep, voffA);
;             PG8_WAIT_V(8); PG8_WAIT_L(0); PG8_BAR; PG8_MMA(0, 0, At, B0); PG8_MMA(0, 1, At, B1); PG8_BAR; PG8_SCHED;
;             PG8_LDA(At, 0, 1); PG8_STAGE(PG8_SB(0, 0), b2, voffB); PG8_STAGE(PG8_SB(0, 1), b2 + hstep, voffB); PG8_STAGE(PG8_SA(0, 0), a2, voffA);
;             PG8_WAIT_V(8); PG8_WAIT_L(0); PG8_BAR; PG8_MMA(1, 0, At, B0); PG8_MMA(1, 1, At, B1); PG8_BAR; PG8_SCHED;
.LBB0_592:
	s_add_i32 s59, s33, 2
	s_add_u32 s6, s30, 0x80
	s_addc_u32 s7, s31, 0
	s_add_i32 s67, 0, 0x10000
	s_cmp_eq_u32 s56, s33
	s_cselect_b32 s35, s11, s7
	s_cselect_b32 s34, s10, s6
	v_add_u32_e32 v147, s67, v144
	s_cselect_b32 s7, s29, s66
	s_cselect_b32 s6, s28, s65
	s_add_i32 s33, 0, 0x14000
	ds_read_b128 v[148:151], v147
	ds_read_b128 v[158:161], v147 offset:1024
	ds_read_b128 v[162:165], v147 offset:2048
	ds_read_b128 v[166:169], v147 offset:3072
	v_add_u32_e32 v147, s33, v144
	ds_read_b128 v[170:173], v147
	ds_read_b128 v[174:177], v147 offset:1024
	ds_read_b128 v[182:185], v147 offset:2048
	ds_read_b128 v[186:189], v147 offset:3072
	s_add_i32 m0, s44, 0xc000
	ds_read_b128 v[190:193], v146
	ds_read_b128 v[194:197], v146 offset:1024
	ds_read_b128 v[198:201], v146 offset:2048
	ds_read_b128 v[202:205], v146 offset:3072
	ds_read_b128 v[206:209], v146 offset:4096
	ds_read_b128 v[210:213], v146 offset:5120
	ds_read_b128 v[214:217], v146 offset:6144
	ds_read_b128 v[218:221], v146 offset:7168
	global_load_lds_dwordx4 v140, s[30:31]
	s_add_i32 m0, s44, 0xe000
	s_nop 0
	global_load_lds_dwordx4 v142, s[30:31]
	s_waitcnt vmcnt(8)
	s_waitcnt lgkmcnt(0)
	s_barrier
	s_setprio 1
	s_waitcnt lgkmcnt(0)
	v_mfma_f32_16x16x32_bf16 v[122:125], v[148:151], v[190:193], v[122:125]
	v_mfma_f32_16x16x32_bf16 v[126:129], v[162:165], v[190:193], v[126:129]
	v_mfma_f32_16x16x32_bf16 v[110:113], v[148:151], v[198:201], v[110:113]
	v_mfma_f32_16x16x32_bf16 v[106:109], v[162:165], v[198:201], v[106:109]
	v_mfma_f32_16x16x32_bf16 v[94:97], v[148:151], v[206:209], v[94:97]
	v_mfma_f32_16x16x32_bf16 v[90:93], v[162:165], v[206:209], v[90:93]
	v_mfma_f32_16x16x32_bf16 v[78:81], v[148:151], v[214:217], v[78:81]
	v_mfma_f32_16x16x32_bf16 v[74:77], v[162:165], v[214:217], v[74:77]
	v_mfma_f32_16x16x32_bf16 v[122:125], v[158:161], v[194:197], v[122:125]
	v_mfma_f32_16x16x32_bf16 v[126:129], v[166:169], v[194:197], v[126:129]
	v_mfma_f32_16x16x32_bf16 v[110:113], v[158:161], v[202:205], v[110:113]
	v_mfma_f32_16x16x32_bf16 v[106:109], v[166:169], v[202:205], v[106:109]
	v_mfma_f32_16x16x32_bf16 v[94:97], v[158:161], v[210:213], v[94:97]
	v_mfma_f32_16x16x32_bf16 v[90:93], v[166:169], v[210:213], v[90:93]
	v_mfma_f32_16x16x32_bf16 v[78:81], v[158:161], v[218:221], v[78:81]
	v_mfma_f32_16x16x32_bf16 v[74:77], v[166:169], v[218:221], v[74:77]
	s_setprio 0
	s_setprio 1
	v_mfma_f32_16x16x32_bf16 v[118:121], v[170:173], v[190:193], v[118:121]
	v_mfma_f32_16x16x32_bf16 v[114:117], v[182:185], v[190:193], v[114:117]
	v_mfma_f32_16x16x32_bf16 v[102:105], v[170:173], v[198:201], v[102:105]
	v_mfma_f32_16x16x32_bf16 v[98:101], v[182:185], v[198:201], v[98:101]
	v_mfma_f32_16x16x32_bf16 v[86:89], v[170:173], v[206:209], v[86:89]
	v_mfma_f32_16x16x32_bf16 v[82:85], v[182:185], v[206:209], v[82:85]
	v_mfma_f32_16x16x32_bf16 v[70:73], v[170:173], v[214:217], v[70:73]
	v_mfma_f32_16x16x32_bf16 v[66:69], v[182:185], v[214:217], v[66:69]
	v_mfma_f32_16x16x32_bf16 v[118:121], v[174:177], v[194:197], v[118:121]
	v_mfma_f32_16x16x32_bf16 v[114:117], v[186:189], v[194:197], v[114:117]
	v_mfma_f32_16x16x32_bf16 v[102:105], v[174:177], v[202:205], v[102:105]
	v_mfma_f32_16x16x32_bf16 v[98:101], v[186:189], v[202:205], v[98:101]
	v_mfma_f32_16x16x32_bf16 v[86:89], v[174:177], v[210:213], v[86:89]
	v_mfma_f32_16x16x32_bf16 v[82:85], v[186:189], v[210:213], v[82:85]
	v_mfma_f32_16x16x32_bf16 v[70:73], v[174:177], v[218:221], v[70:73]
	v_mfma_f32_16x16x32_bf16 v[66:69], v[186:189], v[218:221], v[66:69]
	s_setprio 0
	s_barrier
	s_add_i32 s67, s67, s38
	s_mov_b32 m0, s67
	ds_read_b128 v[190:193], v146 offset:16384
	ds_read_b128 v[194:197], v146 offset:17408
	ds_read_b128 v[198:201], v146 offset:18432
	ds_read_b128 v[202:205], v146 offset:19456
	ds_read_b128 v[206:209], v146 offset:20480
	ds_read_b128 v[210:213], v146 offset:21504
	ds_read_b128 v[214:217], v146 offset:22528
	ds_read_b128 v[218:221], v146 offset:23552
	global_load_lds_dwordx4 v134, s[6:7]
	s_add_i32 m0, s67, 0x2000
	s_add_u32 s100, s6, 0x80
	s_addc_u32 s101, s7, 0
	global_load_lds_dwordx4 v130, s[6:7]
	s_add_u32 s6, s6, s16
	s_addc_u32 s7, s7, s17
	s_add_i32 s33, s33, s38
	s_mov_b32 m0, s33
	s_nop 0
	global_load_lds_dwordx4 v134, s[6:7]
	s_add_i32 m0, s33, 0x2000
	s_nop 0
	global_load_lds_dwordx4 v130, s[6:7]
	s_mov_b32 m0, s44
	s_nop 0
	global_load_lds_dwordx4 v136, s[34:35]
	s_mov_b32 m0, s45
	s_nop 0
	global_load_lds_dwordx4 v132, s[34:35]
	s_waitcnt vmcnt(8)
	s_waitcnt lgkmcnt(0)
	s_barrier
	s_setprio 1
	s_waitcnt lgkmcnt(0)
	v_mfma_f32_16x16x32_bf16 v[62:65], v[148:151], v[190:193], v[62:65]
	v_mfma_f32_16x16x32_bf16 v[58:61], v[162:165], v[190:193], v[58:61]
	v_mfma_f32_16x16x32_bf16 v[46:49], v[148:151], v[198:201], v[46:49]
	v_mfma_f32_16x16x32_bf16 v[42:45], v[162:165], v[198:201], v[42:45]
	v_mfma_f32_16x16x32_bf16 v[30:33], v[148:151], v[206:209], v[30:33]
	v_mfma_f32_16x16x32_bf16 v[26:29], v[162:165], v[206:209], v[26:29]
	v_mfma_f32_16x16x32_bf16 v[14:17], v[148:151], v[214:217], v[14:17]
	v_mfma_f32_16x16x32_bf16 v[10:13], v[162:165], v[214:217], v[10:13]
	v_mfma_f32_16x16x32_bf16 v[62:65], v[158:161], v[194:197], v[62:65]
	v_mfma_f32_16x16x32_bf16 v[58:61], v[166:169], v[194:197], v[58:61]
	v_mfma_f32_16x16x32_bf16 v[46:49], v[158:161], v[202:205], v[46:49]
	v_mfma_f32_16x16x32_bf16 v[42:45], v[166:169], v[202:205], v[42:45]
	v_mfma_f32_16x16x32_bf16 v[30:33], v[158:161], v[210:213], v[30:33]
	v_mfma_f32_16x16x32_bf16 v[26:29], v[166:169], v[210:213], v[26:29]
	v_mfma_f32_16x16x32_bf16 v[14:17], v[158:161], v[218:221], v[14:17]
	v_mfma_f32_16x16x32_bf16 v[10:13], v[166:169], v[218:221], v[10:13]
	s_setprio 0
	s_setprio 1
	v_mfma_f32_16x16x32_bf16 v[54:57], v[170:173], v[190:193], v[54:57]
	v_mfma_f32_16x16x32_bf16 v[50:53], v[182:185], v[190:193], v[50:53]
	v_mfma_f32_16x16x32_bf16 v[38:41], v[170:173], v[198:201], v[38:41]
	v_mfma_f32_16x16x32_bf16 v[34:37], v[182:185], v[198:201], v[34:37]
	v_mfma_f32_16x16x32_bf16 v[22:25], v[170:173], v[206:209], v[22:25]
	v_mfma_f32_16x16x32_bf16 v[18:21], v[182:185], v[206:209], v[18:21]
	v_mfma_f32_16x16x32_bf16 v[6:9], v[170:173], v[214:217], v[6:9]
	v_mfma_f32_16x16x32_bf16 v[2:5], v[182:185], v[214:217], v[2:5]
	v_mfma_f32_16x16x32_bf16 v[54:57], v[174:177], v[194:197], v[54:57]
	v_mfma_f32_16x16x32_bf16 v[50:53], v[186:189], v[194:197], v[50:53]
	v_mfma_f32_16x16x32_bf16 v[38:41], v[174:177], v[202:205], v[38:41]
	v_mfma_f32_16x16x32_bf16 v[34:37], v[186:189], v[202:205], v[34:37]
	v_mfma_f32_16x16x32_bf16 v[22:25], v[174:177], v[210:213], v[22:25]
	v_mfma_f32_16x16x32_bf16 v[18:21], v[186:189], v[210:213], v[18:21]
	v_mfma_f32_16x16x32_bf16 v[6:9], v[174:177], v[218:221], v[6:9]
	v_mfma_f32_16x16x32_bf16 v[2:5], v[186:189], v[218:221], v[2:5]
	s_setprio 0
	s_barrier
; #define PG8_STAGE(bufoff, gbase, voff) do { _Pragma("unroll") for (int _i = 0; _i < 2; ++_i) \
;         __builtin_amdgcn_global_load_lds((const unsigned*)((const char*)(gbase) + (voff)[_i]), (PG8_LAS unsigned*)(lds + (bufoff) + ldsw + _i * 8192), 16, 0, 0); } while (0)
; #define PG8_LDA(dst, b, h) do { _Pragma("unroll") for (int m = 0; m < 4; ++m) _Pragma("unroll") for (int k = 0; k < 2; ++k) dst[m][k] = *(const PG8_LAS bf16x8*)(lds + PG8_SA(b, h) + aoff + m * 2048 + k * 1024); } while (0)
; #define PG8_LDB(dst, b, h) do { _Pragma("unroll") for (int n = 0; n < 2; ++n) _Pragma("unroll") for (int k = 0; k < 2; ++k) dst[n][k] = *(const PG8_LAS bf16x8*)(lds + PG8_SB(b, h) + boff + n * 2048 + k * 1024); } while (0)
; #define PG8_WAIT_V(n) asm volatile("s_waitcnt vmcnt(" #n ")" ::: "memory")
; #define PG8_WAIT_L(n) asm volatile("s_waitcnt lgkmcnt(" #n ")" ::: "memory")
; template <class Epi, class Sched, bool ALIGN_EPI = false, bool SP2 = false>
; __device__ __forceinline__ void gemm_phase(PG8_LAS unsigned char* lds, const Gemm g, const Sched& S, const Epi& E) {
;     ...
;             const char* a2 = last ? nA : cA + (size_t)(t + 2) * kstep; const char* b2 = last ? nB : cB + (size_t)(t + 2) * kstep;
;             const char* a3 = a2 + kstep; const char* b3 = b2 + kstep;
;             if (last && has_next) S.a_ready(nxt);
;             if constexpr (SP2) {
;             PG8_LDB(B0, 0, 0); PG8_LDB(B1, 0, 1); PG8_SCHED; PG8_LDA(At, 0, 0); PG8_STAGE(PG8_SA(1, 1), a1 + hstep, voffA);
;             PG8_WAIT_V(8); PG8_WAIT_L(0); PG8_BAR; PG8_MMA(0, 0, At, B0); PG8_MMA(0, 1, At, B1); PG8_BAR; PG8_SCHED;
;             PG8_LDA(At, 0, 1); PG8_STAGE(PG8_SB(0, 0), b2, voffB); PG8_STAGE(PG8_SB(0, 1), b2 + hstep, voffB); PG8_STAGE(PG8_SA(0, 0), a2, voffA);
;             PG8_WAIT_V(8); PG8_WAIT_L(0); PG8_BAR; PG8_MMA(1, 0, At, B0); PG8_MMA(1, 1, At, B1); PG8_BAR; PG8_SCHED;
;             PG8_LDB(B0, 1, 0); PG8_LDB(B1, 1, 1); PG8_SCHED; PG8_LDA(At, 1, 0); PG8_STAGE(PG8_SA(0, 1), a2 + hstep, voffA);
;             PG8_WAIT_V(8); PG8_WAIT_L(0); PG8_BAR; PG8_MMA(0, 0, At, B0); PG8_MMA(0, 1, At, B1); PG8_BAR; PG8_SCHED;
;             PG8_LDA(At, 1, 1); PG8_STAGE(PG8_SB(1, 0), b3, voffB); PG8_STAGE(PG8_SB(1, 1), b3 + hstep, voffB); PG8_STAGE(PG8_SA(1, 0), a3, voffA);
;             PG8_WAIT_V(8); PG8_WAIT_L(0); PG8_BAR; PG8_MMA(1, 0, At, B0); PG8_MMA(1, 1, At, B1); PG8_BAR; PG8_SCHED;
	s_add_i32 s33, 0, 0x18000
	v_add_u32_e32 v147, s33, v144
	s_add_i32 s67, 0, 0x1c000
	ds_read_b128 v[148:151], v147
	ds_read_b128 v[158:161], v147 offset:1024
	ds_read_b128 v[162:165], v147 offset:2048
	ds_read_b128 v[166:169], v147 offset:3072
	v_add_u32_e32 v147, s67, v144
	ds_read_b128 v[170:173], v147
	ds_read_b128 v[174:177], v147 offset:1024
	ds_read_b128 v[182:185], v147 offset:2048
	ds_read_b128 v[186:189], v147 offset:3072
	s_add_u32 s6, s34, s16
	s_addc_u32 s7, s35, s17
	s_mov_b32 m0, s46
	ds_read_b128 v[190:193], v146 offset:32768
	ds_read_b128 v[194:197], v146 offset:33792
	ds_read_b128 v[198:201], v146 offset:34816
	ds_read_b128 v[202:205], v146 offset:35840
	ds_read_b128 v[206:209], v146 offset:36864
	ds_read_b128 v[210:213], v146 offset:37888
	ds_read_b128 v[214:217], v146 offset:38912
	ds_read_b128 v[218:221], v146 offset:39936
	global_load_lds_dwordx4 v136, s[6:7]
	s_mov_b32 m0, s47
	s_nop 0
	global_load_lds_dwordx4 v132, s[6:7]
	s_waitcnt vmcnt(8)
	s_waitcnt lgkmcnt(0)
	s_barrier
	s_setprio 1
	s_waitcnt lgkmcnt(0)
	v_mfma_f32_16x16x32_bf16 v[122:125], v[148:151], v[190:193], v[122:125]
	v_mfma_f32_16x16x32_bf16 v[126:129], v[162:165], v[190:193], v[126:129]
	v_mfma_f32_16x16x32_bf16 v[110:113], v[148:151], v[198:201], v[110:113]
	v_mfma_f32_16x16x32_bf16 v[106:109], v[162:165], v[198:201], v[106:109]
	v_mfma_f32_16x16x32_bf16 v[94:97], v[148:151], v[206:209], v[94:97]
	v_mfma_f32_16x16x32_bf16 v[90:93], v[162:165], v[206:209], v[90:93]
	v_mfma_f32_16x16x32_bf16 v[78:81], v[148:151], v[214:217], v[78:81]
	v_mfma_f32_16x16x32_bf16 v[74:77], v[162:165], v[214:217], v[74:77]
	v_mfma_f32_16x16x32_bf16 v[122:125], v[158:161], v[194:197], v[122:125]
	v_mfma_f32_16x16x32_bf16 v[126:129], v[166:169], v[194:197], v[126:129]
	v_mfma_f32_16x16x32_bf16 v[110:113], v[158:161], v[202:205], v[110:113]
	v_mfma_f32_16x16x32_bf16 v[106:109], v[166:169], v[202:205], v[106:109]
	v_mfma_f32_16x16x32_bf16 v[94:97], v[158:161], v[210:213], v[94:97]
	v_mfma_f32_16x16x32_bf16 v[90:93], v[166:169], v[210:213], v[90:93]
	v_mfma_f32_16x16x32_bf16 v[78:81], v[158:161], v[218:221], v[78:81]
	v_mfma_f32_16x16x32_bf16 v[74:77], v[166:169], v[218:221], v[74:77]
	s_setprio 0
	s_setprio 1
	v_mfma_f32_16x16x32_bf16 v[118:121], v[170:173], v[190:193], v[118:121]
	v_mfma_f32_16x16x32_bf16 v[114:117], v[182:185], v[190:193], v[114:117]
	v_mfma_f32_16x16x32_bf16 v[102:105], v[170:173], v[198:201], v[102:105]
	v_mfma_f32_16x16x32_bf16 v[98:101], v[182:185], v[198:201], v[98:101]
	v_mfma_f32_16x16x32_bf16 v[86:89], v[170:173], v[206:209], v[86:89]
	v_mfma_f32_16x16x32_bf16 v[82:85], v[182:185], v[206:209], v[82:85]
	v_mfma_f32_16x16x32_bf16 v[70:73], v[170:173], v[214:217], v[70:73]
	v_mfma_f32_16x16x32_bf16 v[66:69], v[182:185], v[214:217], v[66:69]
	v_mfma_f32_16x16x32_bf16 v[118:121], v[174:177], v[194:197], v[118:121]
	v_mfma_f32_16x16x32_bf16 v[114:117], v[186:189], v[194:197], v[114:117]
	v_mfma_f32_16x16x32_bf16 v[102:105], v[174:177], v[202:205], v[102:105]
	v_mfma_f32_16x16x32_bf16 v[98:101], v[186:189], v[202:205], v[98:101]
	v_mfma_f32_16x16x32_bf16 v[86:89], v[174:177], v[210:213], v[86:89]
	v_mfma_f32_16x16x32_bf16 v[82:85], v[186:189], v[210:213], v[82:85]
	v_mfma_f32_16x16x32_bf16 v[70:73], v[174:177], v[218:221], v[70:73]
	v_mfma_f32_16x16x32_bf16 v[66:69], v[186:189], v[218:221], v[66:69]
	s_setprio 0
	s_barrier
	s_add_i32 s6, s33, s38
	s_mov_b32 m0, s6
	ds_read_b128 v[190:193], v146 offset:49152
	ds_read_b128 v[194:197], v146 offset:50176
	ds_read_b128 v[198:201], v146 offset:51200
	ds_read_b128 v[202:205], v146 offset:52224
	ds_read_b128 v[206:209], v146 offset:53248
	ds_read_b128 v[210:213], v146 offset:54272
	ds_read_b128 v[214:217], v146 offset:55296
	ds_read_b128 v[218:221], v146 offset:56320
	global_load_lds_dwordx4 v134, s[100:101]
	s_add_i32 m0, s6, 0x2000
	s_add_i32 s6, s67, s38
	global_load_lds_dwordx4 v130, s[100:101]
	s_add_u32 s100, s100, s16
	s_addc_u32 s101, s101, s17
	s_mov_b32 m0, s6
	s_nop 0
	global_load_lds_dwordx4 v134, s[100:101]
	s_add_i32 m0, s6, 0x2000
	s_nop 0
	global_load_lds_dwordx4 v130, s[100:101]
	s_add_u32 s100, s34, 0x80
	s_addc_u32 s101, s35, 0
	s_mov_b32 m0, s51
	s_nop 0
	global_load_lds_dwordx4 v136, s[100:101]
	s_mov_b32 m0, s54
	s_nop 0
	global_load_lds_dwordx4 v132, s[100:101]
	s_waitcnt vmcnt(8)
	s_waitcnt lgkmcnt(0)
	s_barrier
	s_setprio 1
	s_waitcnt lgkmcnt(0)
	v_mfma_f32_16x16x32_bf16 v[62:65], v[148:151], v[190:193], v[62:65]
	v_mfma_f32_16x16x32_bf16 v[58:61], v[162:165], v[190:193], v[58:61]
	v_mfma_f32_16x16x32_bf16 v[46:49], v[148:151], v[198:201], v[46:49]
	v_mfma_f32_16x16x32_bf16 v[42:45], v[162:165], v[198:201], v[42:45]
	v_mfma_f32_16x16x32_bf16 v[30:33], v[148:151], v[206:209], v[30:33]
	v_mfma_f32_16x16x32_bf16 v[26:29], v[162:165], v[206:209], v[26:29]
	v_mfma_f32_16x16x32_bf16 v[14:17], v[148:151], v[214:217], v[14:17]
	v_mfma_f32_16x16x32_bf16 v[10:13], v[162:165], v[214:217], v[10:13]
	v_mfma_f32_16x16x32_bf16 v[62:65], v[158:161], v[194:197], v[62:65]
	v_mfma_f32_16x16x32_bf16 v[58:61], v[166:169], v[194:197], v[58:61]
	v_mfma_f32_16x16x32_bf16 v[46:49], v[158:161], v[202:205], v[46:49]
	v_mfma_f32_16x16x32_bf16 v[42:45], v[166:169], v[202:205], v[42:45]
	v_mfma_f32_16x16x32_bf16 v[30:33], v[158:161], v[210:213], v[30:33]
	v_mfma_f32_16x16x32_bf16 v[26:29], v[166:169], v[210:213], v[26:29]
	v_mfma_f32_16x16x32_bf16 v[14:17], v[158:161], v[218:221], v[14:17]
	v_mfma_f32_16x16x32_bf16 v[10:13], v[166:169], v[218:221], v[10:13]
	s_setprio 0
	s_setprio 1
	v_mfma_f32_16x16x32_bf16 v[54:57], v[170:173], v[190:193], v[54:57]
	v_mfma_f32_16x16x32_bf16 v[50:53], v[182:185], v[190:193], v[50:53]
	v_mfma_f32_16x16x32_bf16 v[38:41], v[170:173], v[198:201], v[38:41]
	v_mfma_f32_16x16x32_bf16 v[34:37], v[182:185], v[198:201], v[34:37]
	v_mfma_f32_16x16x32_bf16 v[22:25], v[170:173], v[206:209], v[22:25]
	v_mfma_f32_16x16x32_bf16 v[18:21], v[182:185], v[206:209], v[18:21]
	v_mfma_f32_16x16x32_bf16 v[6:9], v[170:173], v[214:217], v[6:9]
	v_mfma_f32_16x16x32_bf16 v[2:5], v[182:185], v[214:217], v[2:5]
	v_mfma_f32_16x16x32_bf16 v[54:57], v[174:177], v[194:197], v[54:57]
	v_mfma_f32_16x16x32_bf16 v[50:53], v[186:189], v[194:197], v[50:53]
	v_mfma_f32_16x16x32_bf16 v[38:41], v[174:177], v[202:205], v[38:41]
	v_mfma_f32_16x16x32_bf16 v[34:37], v[186:189], v[202:205], v[34:37]
	v_mfma_f32_16x16x32_bf16 v[22:25], v[174:177], v[210:213], v[22:25]
	v_mfma_f32_16x16x32_bf16 v[18:21], v[186:189], v[210:213], v[18:21]
	v_mfma_f32_16x16x32_bf16 v[6:9], v[174:177], v[218:221], v[6:9]
	v_mfma_f32_16x16x32_bf16 v[2:5], v[186:189], v[218:221], v[2:5]
	s_setprio 0
	s_barrier
	s_add_u32 s30, s30, 0x100
	s_addc_u32 s31, s31, 0
	s_add_u32 s65, s65, 0x100
	s_addc_u32 s66, s66, 0
	s_cmp_ge_i32 s59, s48
	s_mov_b32 s33, s59
	s_cbranch_scc0 .LBB0_592
	s_movk_i32 s66, 0x700

; #define PG8_STAGE(bufoff, gbase, voff) do { _Pragma("unroll") for (int _i = 0; _i < 2; ++_i) \
;         __builtin_amdgcn_global_load_lds((const unsigned*)((const char*)(gbase) + (voff)[_i]), (PG8_LAS unsigned*)(lds + (bufoff) + ldsw + _i * 8192), 16, 0, 0); } while (0)
; #define PG8_LDA(dst, b, h) do { _Pragma("unroll") for (int m = 0; m < 4; ++m) _Pragma("unroll") for (int k = 0; k < 2; ++k) dst[m][k] = *(const PG8_LAS bf16x8*)(lds + PG8_SA(b, h) + aoff + m * 2048 + k * 1024); } while (0)
; #define PG8_LDB(dst, b, h) do { _Pragma("unroll") for (int n = 0; n < 2; ++n) _Pragma("unroll") for (int k = 0; k < 2; ++k) dst[n][k] = *(const PG8_LAS bf16x8*)(lds + PG8_SB(b, h) + boff + n * 2048 + k * 1024); } while (0)
; #define PG8_MMA(ai, bj, At, Bt) do { __builtin_amdgcn_s_setprio(1); _Pragma("unroll") for (int m = 0; m < 4; ++m) _Pragma("unroll") for (int n = 0; n < 2; ++n) _Pragma("unroll") for (int k = 0; k < 2; ++k) \
;         acc[ai][bj][m][n] = __builtin_amdgcn_mfma_f32_16x16x32_bf16(Bt[n][k], At[m][k], acc[ai][bj][m][n], 0, 0, 0); __builtin_amdgcn_s_setprio(0); } while (0)
; #define PG8_WAIT_V(n) asm volatile("s_waitcnt vmcnt(" #n ")" ::: "memory")
; #define PG8_BAR __builtin_amdgcn_s_barrier()
; template <class Epi, class Sched, bool ALIGN_EPI = false, bool SP2 = false>
; __device__ __forceinline__ void gemm_phase(PG8_LAS unsigned char* lds, const Gemm g, const Sched& S, const Epi& E) {
;     ...
;         for (int t = 0; t < nt; t += 2) {
;             const bool last = (t == nt - 2);
;             const char* a1 = cA + (size_t)(t + 1) * kstep;
;             const char* a2 = last ? nA : cA + (size_t)(t + 2) * kstep; const char* b2 = last ? nB : cB + (size_t)(t + 2) * kstep;
;             const char* a3 = a2 + kstep; const char* b3 = b2 + kstep;
;             if (last && has_next) S.a_ready(nxt);
;             if constexpr (SP2) {
;             PG8_LDB(B0, 0, 0); PG8_LDB(B1, 0, 1); PG8_SCHED; PG8_LDA(At, 0, 0); PG8_STAGE(PG8_SA(1, 1), a1 + hstep, voffA);
;             PG8_WAIT_V(8); PG8_WAIT_L(0); PG8_BAR; PG8_MMA(0, 0, At, B0); PG8_MMA(0, 1, At, B1); PG8_BAR; PG8_SCHED;
;             PG8_LDA(At, 0, 1); PG8_STAGE(PG8_SB(0, 0), b2, voffB); PG8_STAGE(PG8_SB(0, 1), b2 + hstep, voffB); PG8_STAGE(PG8_SA(0, 0), a2, voffA);
;             PG8_WAIT_V(8); PG8_WAIT_L(0); PG8_BAR; PG8_MMA(1, 0, At, B0); PG8_MMA(1, 1, At, B1); PG8_BAR; PG8_SCHED;
.LBB0_1024:
	s_add_i32 s59, s33, 2
	s_add_u32 s6, s40, 0x80
	s_addc_u32 s7, s41, 0
	s_add_i32 s72, 0, 0x10000
	s_cmp_eq_u32 s54, s33
	s_cselect_b32 s43, s13, s7
	s_cselect_b32 s42, s12, s6
	s_cselect_b32 s7, s39, s80
	s_cselect_b32 s6, s38, s79
	s_add_i32 s33, 0, 0x14000
	v_add_u32_e32 v166, s72, v148
	v_add_u32_e32 v178, s33, v148
	ds_read_b128 v[144:147], v166
	ds_read_b128 v[158:161], v166 offset:1024
	ds_read_b128 v[162:165], v166 offset:2048
	ds_read_b128 v[166:169], v166 offset:3072
	ds_read_b128 v[170:173], v178
	ds_read_b128 v[174:177], v178 offset:1024
	ds_read_b128 v[182:185], v178 offset:2048
	ds_read_b128 v[186:189], v178 offset:3072
	s_add_i32 m0, s45, 0xc000
	ds_read_b128 v[190:193], v151
	ds_read_b128 v[194:197], v151 offset:1024
	ds_read_b128 v[198:201], v151 offset:2048
	ds_read_b128 v[202:205], v151 offset:3072
	ds_read_b128 v[206:209], v151 offset:4096
	ds_read_b128 v[210:213], v151 offset:5120
	ds_read_b128 v[214:217], v151 offset:6144
	ds_read_b128 v[218:221], v151 offset:7168
	global_load_lds_dwordx4 v140, s[40:41]
	s_add_i32 m0, s45, 0xe000
	s_nop 0
	global_load_lds_dwordx4 v142, s[40:41]
	s_waitcnt vmcnt(8)
	s_waitcnt lgkmcnt(0)
	s_barrier
	s_setprio 1
	s_waitcnt lgkmcnt(0)
	v_mfma_f32_16x16x32_bf16 v[126:129], v[144:147], v[190:193], v[126:129]
	v_mfma_f32_16x16x32_bf16 v[122:125], v[162:165], v[190:193], v[122:125]
	v_mfma_f32_16x16x32_bf16 v[110:113], v[144:147], v[198:201], v[110:113]
	v_mfma_f32_16x16x32_bf16 v[106:109], v[162:165], v[198:201], v[106:109]
	v_mfma_f32_16x16x32_bf16 v[94:97], v[144:147], v[206:209], v[94:97]
	v_mfma_f32_16x16x32_bf16 v[90:93], v[162:165], v[206:209], v[90:93]
	v_mfma_f32_16x16x32_bf16 v[78:81], v[144:147], v[214:217], v[78:81]
	v_mfma_f32_16x16x32_bf16 v[74:77], v[162:165], v[214:217], v[74:77]
	v_mfma_f32_16x16x32_bf16 v[126:129], v[158:161], v[194:197], v[126:129]
	v_mfma_f32_16x16x32_bf16 v[122:125], v[166:169], v[194:197], v[122:125]
	v_mfma_f32_16x16x32_bf16 v[110:113], v[158:161], v[202:205], v[110:113]
	v_mfma_f32_16x16x32_bf16 v[106:109], v[166:169], v[202:205], v[106:109]
	v_mfma_f32_16x16x32_bf16 v[94:97], v[158:161], v[210:213], v[94:97]
	v_mfma_f32_16x16x32_bf16 v[90:93], v[166:169], v[210:213], v[90:93]
	v_mfma_f32_16x16x32_bf16 v[78:81], v[158:161], v[218:221], v[78:81]
	v_mfma_f32_16x16x32_bf16 v[74:77], v[166:169], v[218:221], v[74:77]
	s_setprio 0
	s_setprio 1
	v_mfma_f32_16x16x32_bf16 v[118:121], v[170:173], v[190:193], v[118:121]
	v_mfma_f32_16x16x32_bf16 v[114:117], v[182:185], v[190:193], v[114:117]
	v_mfma_f32_16x16x32_bf16 v[102:105], v[170:173], v[198:201], v[102:105]
	v_mfma_f32_16x16x32_bf16 v[98:101], v[182:185], v[198:201], v[98:101]
	v_mfma_f32_16x16x32_bf16 v[86:89], v[170:173], v[206:209], v[86:89]
	v_mfma_f32_16x16x32_bf16 v[82:85], v[182:185], v[206:209], v[82:85]
	v_mfma_f32_16x16x32_bf16 v[70:73], v[170:173], v[214:217], v[70:73]
	v_mfma_f32_16x16x32_bf16 v[66:69], v[182:185], v[214:217], v[66:69]
	v_mfma_f32_16x16x32_bf16 v[118:121], v[174:177], v[194:197], v[118:121]
	v_mfma_f32_16x16x32_bf16 v[114:117], v[186:189], v[194:197], v[114:117]
	v_mfma_f32_16x16x32_bf16 v[102:105], v[174:177], v[202:205], v[102:105]
	v_mfma_f32_16x16x32_bf16 v[98:101], v[186:189], v[202:205], v[98:101]
	v_mfma_f32_16x16x32_bf16 v[86:89], v[174:177], v[210:213], v[86:89]
	v_mfma_f32_16x16x32_bf16 v[82:85], v[186:189], v[210:213], v[82:85]
	v_mfma_f32_16x16x32_bf16 v[70:73], v[174:177], v[218:221], v[70:73]
	v_mfma_f32_16x16x32_bf16 v[66:69], v[186:189], v[218:221], v[66:69]
	s_setprio 0
	s_barrier
	s_add_i32 s72, s72, s44
	s_mov_b32 m0, s72
	ds_read_b128 v[190:193], v151 offset:16384
	ds_read_b128 v[194:197], v151 offset:17408
	ds_read_b128 v[198:201], v151 offset:18432
	ds_read_b128 v[202:205], v151 offset:19456
	ds_read_b128 v[206:209], v151 offset:20480
	ds_read_b128 v[210:213], v151 offset:21504
	ds_read_b128 v[214:217], v151 offset:22528
	ds_read_b128 v[218:221], v151 offset:23552
	global_load_lds_dwordx4 v132, s[6:7]
	s_add_i32 m0, s72, 0x2000
	s_add_u32 s100, s6, 0x80
	s_addc_u32 s101, s7, 0
	global_load_lds_dwordx4 v136, s[6:7]
	s_add_u32 s6, s6, s22
	s_addc_u32 s7, s7, s23
	s_add_i32 s33, s33, s44
	s_mov_b32 m0, s33
	s_nop 0
	global_load_lds_dwordx4 v132, s[6:7]
	s_add_i32 m0, s33, 0x2000
	s_nop 0
	global_load_lds_dwordx4 v136, s[6:7]
	s_mov_b32 m0, s45
	s_nop 0
	global_load_lds_dwordx4 v130, s[42:43]
	s_mov_b32 m0, s46
	s_nop 0
	global_load_lds_dwordx4 v134, s[42:43]
	s_waitcnt vmcnt(8)
	s_waitcnt lgkmcnt(0)
	s_barrier
	s_setprio 1
	s_waitcnt lgkmcnt(0)
	v_mfma_f32_16x16x32_bf16 v[62:65], v[144:147], v[190:193], v[62:65]
	v_mfma_f32_16x16x32_bf16 v[58:61], v[162:165], v[190:193], v[58:61]
	v_mfma_f32_16x16x32_bf16 v[46:49], v[144:147], v[198:201], v[46:49]
	v_mfma_f32_16x16x32_bf16 v[42:45], v[162:165], v[198:201], v[42:45]
	v_mfma_f32_16x16x32_bf16 v[30:33], v[144:147], v[206:209], v[30:33]
	v_mfma_f32_16x16x32_bf16 v[26:29], v[162:165], v[206:209], v[26:29]
	v_mfma_f32_16x16x32_bf16 v[14:17], v[144:147], v[214:217], v[14:17]
	v_mfma_f32_16x16x32_bf16 v[10:13], v[162:165], v[214:217], v[10:13]
	v_mfma_f32_16x16x32_bf16 v[62:65], v[158:161], v[194:197], v[62:65]
	v_mfma_f32_16x16x32_bf16 v[58:61], v[166:169], v[194:197], v[58:61]
	v_mfma_f32_16x16x32_bf16 v[46:49], v[158:161], v[202:205], v[46:49]
	v_mfma_f32_16x16x32_bf16 v[42:45], v[166:169], v[202:205], v[42:45]
	v_mfma_f32_16x16x32_bf16 v[30:33], v[158:161], v[210:213], v[30:33]
	v_mfma_f32_16x16x32_bf16 v[26:29], v[166:169], v[210:213], v[26:29]
	v_mfma_f32_16x16x32_bf16 v[14:17], v[158:161], v[218:221], v[14:17]
	v_mfma_f32_16x16x32_bf16 v[10:13], v[166:169], v[218:221], v[10:13]
	s_setprio 0
	s_setprio 1
	v_mfma_f32_16x16x32_bf16 v[54:57], v[170:173], v[190:193], v[54:57]
	v_mfma_f32_16x16x32_bf16 v[50:53], v[182:185], v[190:193], v[50:53]
	v_mfma_f32_16x16x32_bf16 v[38:41], v[170:173], v[198:201], v[38:41]
	v_mfma_f32_16x16x32_bf16 v[34:37], v[182:185], v[198:201], v[34:37]
	v_mfma_f32_16x16x32_bf16 v[22:25], v[170:173], v[206:209], v[22:25]
	v_mfma_f32_16x16x32_bf16 v[18:21], v[182:185], v[206:209], v[18:21]
	v_mfma_f32_16x16x32_bf16 v[6:9], v[170:173], v[214:217], v[6:9]
	v_mfma_f32_16x16x32_bf16 v[2:5], v[182:185], v[214:217], v[2:5]
	v_mfma_f32_16x16x32_bf16 v[54:57], v[174:177], v[194:197], v[54:57]
	v_mfma_f32_16x16x32_bf16 v[50:53], v[186:189], v[194:197], v[50:53]
	v_mfma_f32_16x16x32_bf16 v[38:41], v[174:177], v[202:205], v[38:41]
	v_mfma_f32_16x16x32_bf16 v[34:37], v[186:189], v[202:205], v[34:37]
	v_mfma_f32_16x16x32_bf16 v[22:25], v[174:177], v[210:213], v[22:25]
	v_mfma_f32_16x16x32_bf16 v[18:21], v[186:189], v[210:213], v[18:21]
	v_mfma_f32_16x16x32_bf16 v[6:9], v[174:177], v[218:221], v[6:9]
	v_mfma_f32_16x16x32_bf16 v[2:5], v[186:189], v[218:221], v[2:5]
	s_setprio 0
	s_barrier
; #define PG8_STAGE(bufoff, gbase, voff) do { _Pragma("unroll") for (int _i = 0; _i < 2; ++_i) \
;         __builtin_amdgcn_global_load_lds((const unsigned*)((const char*)(gbase) + (voff)[_i]), (PG8_LAS unsigned*)(lds + (bufoff) + ldsw + _i * 8192), 16, 0, 0); } while (0)
; #define PG8_LDA(dst, b, h) do { _Pragma("unroll") for (int m = 0; m < 4; ++m) _Pragma("unroll") for (int k = 0; k < 2; ++k) dst[m][k] = *(const PG8_LAS bf16x8*)(lds + PG8_SA(b, h) + aoff + m * 2048 + k * 1024); } while (0)
; #define PG8_LDB(dst, b, h) do { _Pragma("unroll") for (int n = 0; n < 2; ++n) _Pragma("unroll") for (int k = 0; k < 2; ++k) dst[n][k] = *(const PG8_LAS bf16x8*)(lds + PG8_SB(b, h) + boff + n * 2048 + k * 1024); } while (0)
; #define PG8_WAIT_V(n) asm volatile("s_waitcnt vmcnt(" #n ")" ::: "memory")
; #define PG8_WAIT_L(n) asm volatile("s_waitcnt lgkmcnt(" #n ")" ::: "memory")
; template <class Epi, class Sched, bool ALIGN_EPI = false, bool SP2 = false>
; __device__ __forceinline__ void gemm_phase(PG8_LAS unsigned char* lds, const Gemm g, const Sched& S, const Epi& E) {
;     ...
;             const char* a2 = last ? nA : cA + (size_t)(t + 2) * kstep; const char* b2 = last ? nB : cB + (size_t)(t + 2) * kstep;
;             const char* a3 = a2 + kstep; const char* b3 = b2 + kstep;
;             if (last && has_next) S.a_ready(nxt);
;             if constexpr (SP2) {
;             PG8_LDB(B0, 0, 0); PG8_LDB(B1, 0, 1); PG8_SCHED; PG8_LDA(At, 0, 0); PG8_STAGE(PG8_SA(1, 1), a1 + hstep, voffA);
;             PG8_WAIT_V(8); PG8_WAIT_L(0); PG8_BAR; PG8_MMA(0, 0, At, B0); PG8_MMA(0, 1, At, B1); PG8_BAR; PG8_SCHED;
;             PG8_LDA(At, 0, 1); PG8_STAGE(PG8_SB(0, 0), b2, voffB); PG8_STAGE(PG8_SB(0, 1), b2 + hstep, voffB); PG8_STAGE(PG8_SA(0, 0), a2, voffA);
;             PG8_WAIT_V(8); PG8_WAIT_L(0); PG8_BAR; PG8_MMA(1, 0, At, B0); PG8_MMA(1, 1, At, B1); PG8_BAR; PG8_SCHED;
;             PG8_LDB(B0, 1, 0); PG8_LDB(B1, 1, 1); PG8_SCHED; PG8_LDA(At, 1, 0); PG8_STAGE(PG8_SA(0, 1), a2 + hstep, voffA);
;             PG8_WAIT_V(8); PG8_WAIT_L(0); PG8_BAR; PG8_MMA(0, 0, At, B0); PG8_MMA(0, 1, At, B1); PG8_BAR; PG8_SCHED;
;             PG8_LDA(At, 1, 1); PG8_STAGE(PG8_SB(1, 0), b3, voffB); PG8_STAGE(PG8_SB(1, 1), b3 + hstep, voffB); PG8_STAGE(PG8_SA(1, 0), a3, voffA);
;             PG8_WAIT_V(8); PG8_WAIT_L(0); PG8_BAR; PG8_MMA(1, 0, At, B0); PG8_MMA(1, 1, At, B1); PG8_BAR; PG8_SCHED;
	s_add_i32 s33, 0, 0x18000
	s_add_i32 s72, 0, 0x1c000
	v_add_u32_e32 v166, s33, v148
	v_add_u32_e32 v181, s72, v148
	ds_read_b128 v[144:147], v166
	ds_read_b128 v[158:161], v166 offset:1024
	ds_read_b128 v[162:165], v166 offset:2048
	ds_read_b128 v[166:169], v166 offset:3072
	ds_read_b128 v[170:173], v181
	ds_read_b128 v[174:177], v181 offset:1024
	ds_read_b128 v[182:185], v181 offset:2048
	ds_read_b128 v[186:189], v181 offset:3072
	s_add_u32 s6, s42, s22
	s_addc_u32 s7, s43, s23
	s_mov_b32 m0, s47
	ds_read_b128 v[190:193], v151 offset:32768
	ds_read_b128 v[194:197], v151 offset:33792
	ds_read_b128 v[198:201], v151 offset:34816
	ds_read_b128 v[202:205], v151 offset:35840
	ds_read_b128 v[206:209], v151 offset:36864
	ds_read_b128 v[210:213], v151 offset:37888
	ds_read_b128 v[214:217], v151 offset:38912
	ds_read_b128 v[218:221], v151 offset:39936
	global_load_lds_dwordx4 v130, s[6:7]
	s_mov_b32 m0, s48
	s_nop 0
	global_load_lds_dwordx4 v134, s[6:7]
	s_waitcnt vmcnt(8)
	s_waitcnt lgkmcnt(0)
	s_barrier
	s_setprio 1
	s_waitcnt lgkmcnt(0)
	v_mfma_f32_16x16x32_bf16 v[126:129], v[144:147], v[190:193], v[126:129]
	v_mfma_f32_16x16x32_bf16 v[122:125], v[162:165], v[190:193], v[122:125]
	v_mfma_f32_16x16x32_bf16 v[110:113], v[144:147], v[198:201], v[110:113]
	v_mfma_f32_16x16x32_bf16 v[106:109], v[162:165], v[198:201], v[106:109]
	v_mfma_f32_16x16x32_bf16 v[94:97], v[144:147], v[206:209], v[94:97]
	v_mfma_f32_16x16x32_bf16 v[90:93], v[162:165], v[206:209], v[90:93]
	v_mfma_f32_16x16x32_bf16 v[78:81], v[144:147], v[214:217], v[78:81]
	v_mfma_f32_16x16x32_bf16 v[74:77], v[162:165], v[214:217], v[74:77]
	v_mfma_f32_16x16x32_bf16 v[126:129], v[158:161], v[194:197], v[126:129]
	v_mfma_f32_16x16x32_bf16 v[122:125], v[166:169], v[194:197], v[122:125]
	v_mfma_f32_16x16x32_bf16 v[110:113], v[158:161], v[202:205], v[110:113]
	v_mfma_f32_16x16x32_bf16 v[106:109], v[166:169], v[202:205], v[106:109]
	v_mfma_f32_16x16x32_bf16 v[94:97], v[158:161], v[210:213], v[94:97]
	v_mfma_f32_16x16x32_bf16 v[90:93], v[166:169], v[210:213], v[90:93]
	v_mfma_f32_16x16x32_bf16 v[78:81], v[158:161], v[218:221], v[78:81]
	v_mfma_f32_16x16x32_bf16 v[74:77], v[166:169], v[218:221], v[74:77]
	s_setprio 0
	s_setprio 1
	v_mfma_f32_16x16x32_bf16 v[118:121], v[170:173], v[190:193], v[118:121]
	v_mfma_f32_16x16x32_bf16 v[114:117], v[182:185], v[190:193], v[114:117]
	v_mfma_f32_16x16x32_bf16 v[102:105], v[170:173], v[198:201], v[102:105]
	v_mfma_f32_16x16x32_bf16 v[98:101], v[182:185], v[198:201], v[98:101]
	v_mfma_f32_16x16x32_bf16 v[86:89], v[170:173], v[206:209], v[86:89]
	v_mfma_f32_16x16x32_bf16 v[82:85], v[182:185], v[206:209], v[82:85]
	v_mfma_f32_16x16x32_bf16 v[70:73], v[170:173], v[214:217], v[70:73]
	v_mfma_f32_16x16x32_bf16 v[66:69], v[182:185], v[214:217], v[66:69]
	v_mfma_f32_16x16x32_bf16 v[118:121], v[174:177], v[194:197], v[118:121]
	v_mfma_f32_16x16x32_bf16 v[114:117], v[186:189], v[194:197], v[114:117]
	v_mfma_f32_16x16x32_bf16 v[102:105], v[174:177], v[202:205], v[102:105]
	v_mfma_f32_16x16x32_bf16 v[98:101], v[186:189], v[202:205], v[98:101]
	v_mfma_f32_16x16x32_bf16 v[86:89], v[174:177], v[210:213], v[86:89]
	v_mfma_f32_16x16x32_bf16 v[82:85], v[186:189], v[210:213], v[82:85]
	v_mfma_f32_16x16x32_bf16 v[70:73], v[174:177], v[218:221], v[70:73]
	v_mfma_f32_16x16x32_bf16 v[66:69], v[186:189], v[218:221], v[66:69]
	s_setprio 0
	s_barrier
	s_add_i32 s6, s33, s44
	s_mov_b32 m0, s6
	ds_read_b128 v[190:193], v151 offset:49152
	ds_read_b128 v[194:197], v151 offset:50176
	ds_read_b128 v[198:201], v151 offset:51200
	ds_read_b128 v[202:205], v151 offset:52224
	ds_read_b128 v[206:209], v151 offset:53248
	ds_read_b128 v[210:213], v151 offset:54272
	ds_read_b128 v[214:217], v151 offset:55296
	ds_read_b128 v[218:221], v151 offset:56320
	global_load_lds_dwordx4 v132, s[100:101]
	s_add_i32 m0, s6, 0x2000
	s_add_i32 s6, s72, s44
	global_load_lds_dwordx4 v136, s[100:101]
	s_add_u32 s100, s100, s22
	s_addc_u32 s101, s101, s23
	s_mov_b32 m0, s6
	s_nop 0
	global_load_lds_dwordx4 v132, s[100:101]
	s_add_i32 m0, s6, 0x2000
	s_nop 0
	global_load_lds_dwordx4 v136, s[100:101]
	s_add_u32 s100, s42, 0x80
	s_addc_u32 s101, s43, 0
	s_mov_b32 m0, s50
	s_nop 0
	global_load_lds_dwordx4 v130, s[100:101]
	s_mov_b32 m0, s51
	s_nop 0
	global_load_lds_dwordx4 v134, s[100:101]
	s_waitcnt vmcnt(8)
	s_waitcnt lgkmcnt(0)
	s_barrier
	s_setprio 1
	s_waitcnt lgkmcnt(0)
	v_mfma_f32_16x16x32_bf16 v[62:65], v[144:147], v[190:193], v[62:65]
	v_mfma_f32_16x16x32_bf16 v[58:61], v[162:165], v[190:193], v[58:61]
	v_mfma_f32_16x16x32_bf16 v[46:49], v[144:147], v[198:201], v[46:49]
	v_mfma_f32_16x16x32_bf16 v[42:45], v[162:165], v[198:201], v[42:45]
	v_mfma_f32_16x16x32_bf16 v[30:33], v[144:147], v[206:209], v[30:33]
	v_mfma_f32_16x16x32_bf16 v[26:29], v[162:165], v[206:209], v[26:29]
	v_mfma_f32_16x16x32_bf16 v[14:17], v[144:147], v[214:217], v[14:17]
	v_mfma_f32_16x16x32_bf16 v[10:13], v[162:165], v[214:217], v[10:13]
	v_mfma_f32_16x16x32_bf16 v[62:65], v[158:161], v[194:197], v[62:65]
	v_mfma_f32_16x16x32_bf16 v[58:61], v[166:169], v[194:197], v[58:61]
	v_mfma_f32_16x16x32_bf16 v[46:49], v[158:161], v[202:205], v[46:49]
	v_mfma_f32_16x16x32_bf16 v[42:45], v[166:169], v[202:205], v[42:45]
	v_mfma_f32_16x16x32_bf16 v[30:33], v[158:161], v[210:213], v[30:33]
	v_mfma_f32_16x16x32_bf16 v[26:29], v[166:169], v[210:213], v[26:29]
	v_mfma_f32_16x16x32_bf16 v[14:17], v[158:161], v[218:221], v[14:17]
	v_mfma_f32_16x16x32_bf16 v[10:13], v[166:169], v[218:221], v[10:13]
	s_setprio 0
	s_setprio 1
	v_mfma_f32_16x16x32_bf16 v[54:57], v[170:173], v[190:193], v[54:57]
	v_mfma_f32_16x16x32_bf16 v[50:53], v[182:185], v[190:193], v[50:53]
	v_mfma_f32_16x16x32_bf16 v[38:41], v[170:173], v[198:201], v[38:41]
	v_mfma_f32_16x16x32_bf16 v[34:37], v[182:185], v[198:201], v[34:37]
	v_mfma_f32_16x16x32_bf16 v[22:25], v[170:173], v[206:209], v[22:25]
	v_mfma_f32_16x16x32_bf16 v[18:21], v[182:185], v[206:209], v[18:21]
	v_mfma_f32_16x16x32_bf16 v[6:9], v[170:173], v[214:217], v[6:9]
	v_mfma_f32_16x16x32_bf16 v[2:5], v[182:185], v[214:217], v[2:5]
	v_mfma_f32_16x16x32_bf16 v[54:57], v[174:177], v[194:197], v[54:57]
	v_mfma_f32_16x16x32_bf16 v[50:53], v[186:189], v[194:197], v[50:53]
	v_mfma_f32_16x16x32_bf16 v[38:41], v[174:177], v[202:205], v[38:41]
	v_mfma_f32_16x16x32_bf16 v[34:37], v[186:189], v[202:205], v[34:37]
	v_mfma_f32_16x16x32_bf16 v[22:25], v[174:177], v[210:213], v[22:25]
	v_mfma_f32_16x16x32_bf16 v[18:21], v[186:189], v[210:213], v[18:21]
	v_mfma_f32_16x16x32_bf16 v[6:9], v[174:177], v[218:221], v[6:9]
	v_mfma_f32_16x16x32_bf16 v[2:5], v[186:189], v[218:221], v[2:5]
	s_setprio 0
	s_barrier
	s_add_u32 s40, s40, 0x100
	s_addc_u32 s41, s41, 0
	s_add_u32 s79, s79, 0x100
	s_addc_u32 s80, s80, 0
	s_cmp_ge_i32 s59, s49
	s_mov_b32 s33, s59
	s_cbranch_scc0 .LBB0_1024

; #define PG8_STAGE(bufoff, gbase, voff) do { _Pragma("unroll") for (int _i = 0; _i < 2; ++_i) \
;         __builtin_amdgcn_global_load_lds((const unsigned*)((const char*)(gbase) + (voff)[_i]), (PG8_LAS unsigned*)(lds + (bufoff) + ldsw + _i * 8192), 16, 0, 0); } while (0)
; #define PG8_LDA(dst, b, h) do { _Pragma("unroll") for (int m = 0; m < 4; ++m) _Pragma("unroll") for (int k = 0; k < 2; ++k) dst[m][k] = *(const PG8_LAS bf16x8*)(lds + PG8_SA(b, h) + aoff + m * 2048 + k * 1024); } while (0)
; #define PG8_LDB(dst, b, h) do { _Pragma("unroll") for (int n = 0; n < 2; ++n) _Pragma("unroll") for (int k = 0; k < 2; ++k) dst[n][k] = *(const PG8_LAS bf16x8*)(lds + PG8_SB(b, h) + boff + n * 2048 + k * 1024); } while (0)
; #define PG8_MMA(ai, bj, At, Bt) do { __builtin_amdgcn_s_setprio(1); _Pragma("unroll") for (int m = 0; m < 4; ++m) _Pragma("unroll") for (int n = 0; n < 2; ++n) _Pragma("unroll") for (int k = 0; k < 2; ++k) \
;         acc[ai][bj][m][n] = __builtin_amdgcn_mfma_f32_16x16x32_bf16(Bt[n][k], At[m][k], acc[ai][bj][m][n], 0, 0, 0); __builtin_amdgcn_s_setprio(0); } while (0)
; #define PG8_WAIT_V(n) asm volatile("s_waitcnt vmcnt(" #n ")" ::: "memory")
; #define PG8_BAR __builtin_amdgcn_s_barrier()
; template <class Epi, class Sched, bool ALIGN_EPI = false, bool SP2 = false>
; __device__ __forceinline__ void gemm_phase(PG8_LAS unsigned char* lds, const Gemm g, const Sched& S, const Epi& E) {
;     ...
;         for (int t = 0; t < nt; t += 2) {
;             const bool last = (t == nt - 2);
;             const char* a1 = cA + (size_t)(t + 1) * kstep;
;             const char* a2 = last ? nA : cA + (size_t)(t + 2) * kstep; const char* b2 = last ? nB : cB + (size_t)(t + 2) * kstep;
;             const char* a3 = a2 + kstep; const char* b3 = b2 + kstep;
;             if (last && has_next) S.a_ready(nxt);
;             if constexpr (SP2) {
;             PG8_LDB(B0, 0, 0); PG8_LDB(B1, 0, 1); PG8_SCHED; PG8_LDA(At, 0, 0); PG8_STAGE(PG8_SA(1, 1), a1 + hstep, voffA);
;             PG8_WAIT_V(8); PG8_WAIT_L(0); PG8_BAR; PG8_MMA(0, 0, At, B0); PG8_MMA(0, 1, At, B1); PG8_BAR; PG8_SCHED;
;             PG8_LDA(At, 0, 1); PG8_STAGE(PG8_SB(0, 0), b2, voffB); PG8_STAGE(PG8_SB(0, 1), b2 + hstep, voffB); PG8_STAGE(PG8_SA(0, 0), a2, voffA);
;             PG8_WAIT_V(8); PG8_WAIT_L(0); PG8_BAR; PG8_MMA(1, 0, At, B0); PG8_MMA(1, 1, At, B1); PG8_BAR; PG8_SCHED;
.LBB0_1130:
	s_add_i32 s59, s33, 2
	s_add_u32 s6, s34, 0x80
	s_addc_u32 s7, s35, 0
	s_add_i32 s72, 0, 0x10000
	s_cmp_eq_u32 s65, s33
	s_cselect_b32 s37, s11, s7
	s_cselect_b32 s36, s10, s6
	v_add_u32_e32 v148, s72, v150
	s_cselect_b32 s7, s31, s54
	s_cselect_b32 s6, s30, s2
	s_add_i32 s33, 0, 0x14000
	ds_read_b128 v[144:147], v148
	ds_read_b128 v[160:163], v148 offset:1024
	ds_read_b128 v[164:167], v148 offset:2048
	ds_read_b128 v[168:171], v148 offset:3072
	v_add_u32_e32 v148, s33, v150
	ds_read_b128 v[172:175], v148
	ds_read_b128 v[176:179], v148 offset:1024
	ds_read_b128 v[182:185], v148 offset:2048
	ds_read_b128 v[186:189], v148 offset:3072
	s_add_i32 m0, s49, 0xc000
	ds_read_b128 v[190:193], v158
	ds_read_b128 v[194:197], v158 offset:1024
	ds_read_b128 v[198:201], v158 offset:2048
	ds_read_b128 v[202:205], v158 offset:3072
	ds_read_b128 v[206:209], v158 offset:4096
	ds_read_b128 v[210:213], v158 offset:5120
	ds_read_b128 v[214:217], v158 offset:6144
	ds_read_b128 v[218:221], v158 offset:7168
	global_load_lds_dwordx4 v140, s[34:35]
	s_add_i32 m0, s49, 0xe000
	s_nop 0
	global_load_lds_dwordx4 v142, s[34:35]
	s_waitcnt vmcnt(8)
	s_waitcnt lgkmcnt(0)
	s_barrier
	s_setprio 1
	s_waitcnt lgkmcnt(0)
	v_mfma_f32_16x16x32_bf16 v[122:125], v[144:147], v[190:193], v[122:125]
	v_mfma_f32_16x16x32_bf16 v[126:129], v[164:167], v[190:193], v[126:129]
	v_mfma_f32_16x16x32_bf16 v[110:113], v[144:147], v[198:201], v[110:113]
	v_mfma_f32_16x16x32_bf16 v[106:109], v[164:167], v[198:201], v[106:109]
	v_mfma_f32_16x16x32_bf16 v[94:97], v[144:147], v[206:209], v[94:97]
	v_mfma_f32_16x16x32_bf16 v[90:93], v[164:167], v[206:209], v[90:93]
	v_mfma_f32_16x16x32_bf16 v[78:81], v[144:147], v[214:217], v[78:81]
	v_mfma_f32_16x16x32_bf16 v[74:77], v[164:167], v[214:217], v[74:77]
	v_mfma_f32_16x16x32_bf16 v[122:125], v[160:163], v[194:197], v[122:125]
	v_mfma_f32_16x16x32_bf16 v[126:129], v[168:171], v[194:197], v[126:129]
	v_mfma_f32_16x16x32_bf16 v[110:113], v[160:163], v[202:205], v[110:113]
	v_mfma_f32_16x16x32_bf16 v[106:109], v[168:171], v[202:205], v[106:109]
	v_mfma_f32_16x16x32_bf16 v[94:97], v[160:163], v[210:213], v[94:97]
	v_mfma_f32_16x16x32_bf16 v[90:93], v[168:171], v[210:213], v[90:93]
	v_mfma_f32_16x16x32_bf16 v[78:81], v[160:163], v[218:221], v[78:81]
	v_mfma_f32_16x16x32_bf16 v[74:77], v[168:171], v[218:221], v[74:77]
	s_setprio 0
	s_setprio 1
	v_mfma_f32_16x16x32_bf16 v[118:121], v[172:175], v[190:193], v[118:121]
	v_mfma_f32_16x16x32_bf16 v[114:117], v[182:185], v[190:193], v[114:117]
	v_mfma_f32_16x16x32_bf16 v[102:105], v[172:175], v[198:201], v[102:105]
	v_mfma_f32_16x16x32_bf16 v[98:101], v[182:185], v[198:201], v[98:101]
	v_mfma_f32_16x16x32_bf16 v[86:89], v[172:175], v[206:209], v[86:89]
	v_mfma_f32_16x16x32_bf16 v[82:85], v[182:185], v[206:209], v[82:85]
	v_mfma_f32_16x16x32_bf16 v[70:73], v[172:175], v[214:217], v[70:73]
	v_mfma_f32_16x16x32_bf16 v[66:69], v[182:185], v[214:217], v[66:69]
	v_mfma_f32_16x16x32_bf16 v[118:121], v[176:179], v[194:197], v[118:121]
	v_mfma_f32_16x16x32_bf16 v[114:117], v[186:189], v[194:197], v[114:117]
	v_mfma_f32_16x16x32_bf16 v[102:105], v[176:179], v[202:205], v[102:105]
	v_mfma_f32_16x16x32_bf16 v[98:101], v[186:189], v[202:205], v[98:101]
	v_mfma_f32_16x16x32_bf16 v[86:89], v[176:179], v[210:213], v[86:89]
	v_mfma_f32_16x16x32_bf16 v[82:85], v[186:189], v[210:213], v[82:85]
	v_mfma_f32_16x16x32_bf16 v[70:73], v[176:179], v[218:221], v[70:73]
	v_mfma_f32_16x16x32_bf16 v[66:69], v[186:189], v[218:221], v[66:69]
	s_setprio 0
	s_barrier
	s_add_i32 s72, s72, s43
	s_mov_b32 m0, s72
	ds_read_b128 v[190:193], v158 offset:16384
	ds_read_b128 v[194:197], v158 offset:17408
	ds_read_b128 v[198:201], v158 offset:18432
	ds_read_b128 v[202:205], v158 offset:19456
	ds_read_b128 v[206:209], v158 offset:20480
	ds_read_b128 v[210:213], v158 offset:21504
	ds_read_b128 v[214:217], v158 offset:22528
	ds_read_b128 v[218:221], v158 offset:23552
	global_load_lds_dwordx4 v134, s[6:7]
	s_add_i32 m0, s72, 0x2000
	s_add_u32 s100, s6, 0x80
	s_addc_u32 s101, s7, 0
	global_load_lds_dwordx4 v130, s[6:7]
	s_add_u32 s6, s6, s16
	s_addc_u32 s7, s7, s17
	s_add_i32 s33, s33, s43
	s_mov_b32 m0, s33
	s_nop 0
	global_load_lds_dwordx4 v134, s[6:7]
	s_add_i32 m0, s33, 0x2000
	s_nop 0
	global_load_lds_dwordx4 v130, s[6:7]
	s_mov_b32 m0, s49
	s_nop 0
	global_load_lds_dwordx4 v136, s[36:37]
	s_mov_b32 m0, s50
	s_nop 0
	global_load_lds_dwordx4 v132, s[36:37]
	s_waitcnt vmcnt(8)
	s_waitcnt lgkmcnt(0)
	s_barrier
	s_setprio 1
	s_waitcnt lgkmcnt(0)
	v_mfma_f32_16x16x32_bf16 v[62:65], v[144:147], v[190:193], v[62:65]
	v_mfma_f32_16x16x32_bf16 v[58:61], v[164:167], v[190:193], v[58:61]
	v_mfma_f32_16x16x32_bf16 v[46:49], v[144:147], v[198:201], v[46:49]
	v_mfma_f32_16x16x32_bf16 v[42:45], v[164:167], v[198:201], v[42:45]
	v_mfma_f32_16x16x32_bf16 v[30:33], v[144:147], v[206:209], v[30:33]
	v_mfma_f32_16x16x32_bf16 v[26:29], v[164:167], v[206:209], v[26:29]
	v_mfma_f32_16x16x32_bf16 v[14:17], v[144:147], v[214:217], v[14:17]
	v_mfma_f32_16x16x32_bf16 v[10:13], v[164:167], v[214:217], v[10:13]
	v_mfma_f32_16x16x32_bf16 v[62:65], v[160:163], v[194:197], v[62:65]
	v_mfma_f32_16x16x32_bf16 v[58:61], v[168:171], v[194:197], v[58:61]
	v_mfma_f32_16x16x32_bf16 v[46:49], v[160:163], v[202:205], v[46:49]
	v_mfma_f32_16x16x32_bf16 v[42:45], v[168:171], v[202:205], v[42:45]
	v_mfma_f32_16x16x32_bf16 v[30:33], v[160:163], v[210:213], v[30:33]
	v_mfma_f32_16x16x32_bf16 v[26:29], v[168:171], v[210:213], v[26:29]
	v_mfma_f32_16x16x32_bf16 v[14:17], v[160:163], v[218:221], v[14:17]
	v_mfma_f32_16x16x32_bf16 v[10:13], v[168:171], v[218:221], v[10:13]
	s_setprio 0
	s_setprio 1
	v_mfma_f32_16x16x32_bf16 v[54:57], v[172:175], v[190:193], v[54:57]
	v_mfma_f32_16x16x32_bf16 v[50:53], v[182:185], v[190:193], v[50:53]
	v_mfma_f32_16x16x32_bf16 v[38:41], v[172:175], v[198:201], v[38:41]
	v_mfma_f32_16x16x32_bf16 v[34:37], v[182:185], v[198:201], v[34:37]
	v_mfma_f32_16x16x32_bf16 v[22:25], v[172:175], v[206:209], v[22:25]
	v_mfma_f32_16x16x32_bf16 v[18:21], v[182:185], v[206:209], v[18:21]
	v_mfma_f32_16x16x32_bf16 v[6:9], v[172:175], v[214:217], v[6:9]
	v_mfma_f32_16x16x32_bf16 v[2:5], v[182:185], v[214:217], v[2:5]
	v_mfma_f32_16x16x32_bf16 v[54:57], v[176:179], v[194:197], v[54:57]
	v_mfma_f32_16x16x32_bf16 v[50:53], v[186:189], v[194:197], v[50:53]
	v_mfma_f32_16x16x32_bf16 v[38:41], v[176:179], v[202:205], v[38:41]
	v_mfma_f32_16x16x32_bf16 v[34:37], v[186:189], v[202:205], v[34:37]
	v_mfma_f32_16x16x32_bf16 v[22:25], v[176:179], v[210:213], v[22:25]
	v_mfma_f32_16x16x32_bf16 v[18:21], v[186:189], v[210:213], v[18:21]
	v_mfma_f32_16x16x32_bf16 v[6:9], v[176:179], v[218:221], v[6:9]
	v_mfma_f32_16x16x32_bf16 v[2:5], v[186:189], v[218:221], v[2:5]
	s_setprio 0
	s_barrier
; #define PG8_STAGE(bufoff, gbase, voff) do { _Pragma("unroll") for (int _i = 0; _i < 2; ++_i) \
;         __builtin_amdgcn_global_load_lds((const unsigned*)((const char*)(gbase) + (voff)[_i]), (PG8_LAS unsigned*)(lds + (bufoff) + ldsw + _i * 8192), 16, 0, 0); } while (0)
; #define PG8_LDA(dst, b, h) do { _Pragma("unroll") for (int m = 0; m < 4; ++m) _Pragma("unroll") for (int k = 0; k < 2; ++k) dst[m][k] = *(const PG8_LAS bf16x8*)(lds + PG8_SA(b, h) + aoff + m * 2048 + k * 1024); } while (0)
; #define PG8_LDB(dst, b, h) do { _Pragma("unroll") for (int n = 0; n < 2; ++n) _Pragma("unroll") for (int k = 0; k < 2; ++k) dst[n][k] = *(const PG8_LAS bf16x8*)(lds + PG8_SB(b, h) + boff + n * 2048 + k * 1024); } while (0)
; #define PG8_MMA(ai, bj, At, Bt) do { __builtin_amdgcn_s_setprio(1); _Pragma("unroll") for (int m = 0; m < 4; ++m) _Pragma("unroll") for (int n = 0; n < 2; ++n) _Pragma("unroll") for (int k = 0; k < 2; ++k) \
;         acc[ai][bj][m][n] = __builtin_amdgcn_mfma_f32_16x16x32_bf16(Bt[n][k], At[m][k], acc[ai][bj][m][n], 0, 0, 0); __builtin_amdgcn_s_setprio(0); } while (0)
; #define PG8_WAIT_V(n) asm volatile("s_waitcnt vmcnt(" #n ")" ::: "memory")
; #define PG8_WAIT_L(n) asm volatile("s_waitcnt lgkmcnt(" #n ")" ::: "memory")
; #define PG8_BAR __builtin_amdgcn_s_barrier()
; #define PG8_SCHED __builtin_amdgcn_sched_barrier(0)
; template <class Epi, class Sched, bool ALIGN_EPI = false, bool SP2 = false>
; __device__ __forceinline__ void gemm_phase(PG8_LAS unsigned char* lds, const Gemm g, const Sched& S, const Epi& E) {
;     ...
;             PG8_LDB(B0, 1, 0); PG8_LDB(B1, 1, 1); PG8_SCHED; PG8_LDA(At, 1, 0); PG8_STAGE(PG8_SA(0, 1), a2 + hstep, voffA);
;             PG8_WAIT_V(8); PG8_WAIT_L(0); PG8_BAR; PG8_MMA(0, 0, At, B0); PG8_MMA(0, 1, At, B1); PG8_BAR; PG8_SCHED;
;             PG8_LDA(At, 1, 1); PG8_STAGE(PG8_SB(1, 0), b3, voffB); PG8_STAGE(PG8_SB(1, 1), b3 + hstep, voffB); PG8_STAGE(PG8_SA(1, 0), a3, voffA);
;             PG8_WAIT_V(8); PG8_WAIT_L(0); PG8_BAR; PG8_MMA(1, 0, At, B0); PG8_MMA(1, 1, At, B1); PG8_BAR; PG8_SCHED;
	s_add_i32 s33, 0, 0x18000
	v_add_u32_e32 v159, s33, v150
	s_add_i32 s72, 0, 0x1c000
	ds_read_b128 v[144:147], v159
	ds_read_b128 v[160:163], v159 offset:1024
	ds_read_b128 v[164:167], v159 offset:2048
	ds_read_b128 v[168:171], v159 offset:3072
	v_add_u32_e32 v159, s72, v150
	ds_read_b128 v[172:175], v159
	ds_read_b128 v[176:179], v159 offset:1024
	ds_read_b128 v[182:185], v159 offset:2048
	ds_read_b128 v[186:189], v159 offset:3072
	s_add_u32 s6, s36, s16
	s_addc_u32 s7, s37, s17
	s_mov_b32 m0, s51
	ds_read_b128 v[190:193], v158 offset:32768
	ds_read_b128 v[194:197], v158 offset:33792
	ds_read_b128 v[198:201], v158 offset:34816
	ds_read_b128 v[202:205], v158 offset:35840
	ds_read_b128 v[206:209], v158 offset:36864
	ds_read_b128 v[210:213], v158 offset:37888
	ds_read_b128 v[214:217], v158 offset:38912
	ds_read_b128 v[218:221], v158 offset:39936
	global_load_lds_dwordx4 v136, s[6:7]
	s_mov_b32 m0, s56
	s_nop 0
	global_load_lds_dwordx4 v132, s[6:7]
	s_waitcnt vmcnt(8)
	s_waitcnt lgkmcnt(0)
	s_barrier
	s_setprio 1
	s_waitcnt lgkmcnt(0)
	v_mfma_f32_16x16x32_bf16 v[122:125], v[144:147], v[190:193], v[122:125]
	v_mfma_f32_16x16x32_bf16 v[126:129], v[164:167], v[190:193], v[126:129]
	v_mfma_f32_16x16x32_bf16 v[110:113], v[144:147], v[198:201], v[110:113]
	v_mfma_f32_16x16x32_bf16 v[106:109], v[164:167], v[198:201], v[106:109]
	v_mfma_f32_16x16x32_bf16 v[94:97], v[144:147], v[206:209], v[94:97]
	v_mfma_f32_16x16x32_bf16 v[90:93], v[164:167], v[206:209], v[90:93]
	v_mfma_f32_16x16x32_bf16 v[78:81], v[144:147], v[214:217], v[78:81]
	v_mfma_f32_16x16x32_bf16 v[74:77], v[164:167], v[214:217], v[74:77]
	v_mfma_f32_16x16x32_bf16 v[122:125], v[160:163], v[194:197], v[122:125]
	v_mfma_f32_16x16x32_bf16 v[126:129], v[168:171], v[194:197], v[126:129]
	v_mfma_f32_16x16x32_bf16 v[110:113], v[160:163], v[202:205], v[110:113]
	v_mfma_f32_16x16x32_bf16 v[106:109], v[168:171], v[202:205], v[106:109]
	v_mfma_f32_16x16x32_bf16 v[94:97], v[160:163], v[210:213], v[94:97]
	v_mfma_f32_16x16x32_bf16 v[90:93], v[168:171], v[210:213], v[90:93]
	v_mfma_f32_16x16x32_bf16 v[78:81], v[160:163], v[218:221], v[78:81]
	v_mfma_f32_16x16x32_bf16 v[74:77], v[168:171], v[218:221], v[74:77]
	s_setprio 0
	s_setprio 1
	v_mfma_f32_16x16x32_bf16 v[118:121], v[172:175], v[190:193], v[118:121]
	v_mfma_f32_16x16x32_bf16 v[114:117], v[182:185], v[190:193], v[114:117]
	v_mfma_f32_16x16x32_bf16 v[102:105], v[172:175], v[198:201], v[102:105]
	v_mfma_f32_16x16x32_bf16 v[98:101], v[182:185], v[198:201], v[98:101]
	v_mfma_f32_16x16x32_bf16 v[86:89], v[172:175], v[206:209], v[86:89]
	v_mfma_f32_16x16x32_bf16 v[82:85], v[182:185], v[206:209], v[82:85]
	v_mfma_f32_16x16x32_bf16 v[70:73], v[172:175], v[214:217], v[70:73]
	v_mfma_f32_16x16x32_bf16 v[66:69], v[182:185], v[214:217], v[66:69]
	v_mfma_f32_16x16x32_bf16 v[118:121], v[176:179], v[194:197], v[118:121]
	v_mfma_f32_16x16x32_bf16 v[114:117], v[186:189], v[194:197], v[114:117]
	v_mfma_f32_16x16x32_bf16 v[102:105], v[176:179], v[202:205], v[102:105]
	v_mfma_f32_16x16x32_bf16 v[98:101], v[186:189], v[202:205], v[98:101]
	v_mfma_f32_16x16x32_bf16 v[86:89], v[176:179], v[210:213], v[86:89]
	v_mfma_f32_16x16x32_bf16 v[82:85], v[186:189], v[210:213], v[82:85]
	v_mfma_f32_16x16x32_bf16 v[70:73], v[176:179], v[218:221], v[70:73]
	v_mfma_f32_16x16x32_bf16 v[66:69], v[186:189], v[218:221], v[66:69]
	s_setprio 0
	s_barrier
	s_add_i32 s6, s33, s43
	s_mov_b32 m0, s6
	ds_read_b128 v[190:193], v158 offset:49152
	ds_read_b128 v[194:197], v158 offset:50176
	ds_read_b128 v[198:201], v158 offset:51200
	ds_read_b128 v[202:205], v158 offset:52224
	ds_read_b128 v[206:209], v158 offset:53248
	ds_read_b128 v[210:213], v158 offset:54272
	ds_read_b128 v[214:217], v158 offset:55296
	ds_read_b128 v[218:221], v158 offset:56320
	global_load_lds_dwordx4 v134, s[100:101]
	s_add_i32 m0, s6, 0x2000
	s_add_i32 s6, s72, s43
	global_load_lds_dwordx4 v130, s[100:101]
	s_add_u32 s100, s100, s16
	s_addc_u32 s101, s101, s17
	s_mov_b32 m0, s6
	s_nop 0
	global_load_lds_dwordx4 v134, s[100:101]
	s_add_i32 m0, s6, 0x2000
	s_nop 0
	global_load_lds_dwordx4 v130, s[100:101]
	s_add_u32 s100, s36, 0x80
	s_addc_u32 s101, s37, 0
	s_mov_b32 m0, s60
	s_nop 0
	global_load_lds_dwordx4 v136, s[100:101]
	s_mov_b32 m0, s64
	s_nop 0
	global_load_lds_dwordx4 v132, s[100:101]
	s_waitcnt vmcnt(8)
	s_waitcnt lgkmcnt(0)
	s_barrier
	s_setprio 1
	s_waitcnt lgkmcnt(0)
	v_mfma_f32_16x16x32_bf16 v[62:65], v[144:147], v[190:193], v[62:65]
	v_mfma_f32_16x16x32_bf16 v[58:61], v[164:167], v[190:193], v[58:61]
	v_mfma_f32_16x16x32_bf16 v[46:49], v[144:147], v[198:201], v[46:49]
	v_mfma_f32_16x16x32_bf16 v[42:45], v[164:167], v[198:201], v[42:45]
	v_mfma_f32_16x16x32_bf16 v[30:33], v[144:147], v[206:209], v[30:33]
	v_mfma_f32_16x16x32_bf16 v[26:29], v[164:167], v[206:209], v[26:29]
	v_mfma_f32_16x16x32_bf16 v[14:17], v[144:147], v[214:217], v[14:17]
	v_mfma_f32_16x16x32_bf16 v[10:13], v[164:167], v[214:217], v[10:13]
	v_mfma_f32_16x16x32_bf16 v[62:65], v[160:163], v[194:197], v[62:65]
	v_mfma_f32_16x16x32_bf16 v[58:61], v[168:171], v[194:197], v[58:61]
	v_mfma_f32_16x16x32_bf16 v[46:49], v[160:163], v[202:205], v[46:49]
	v_mfma_f32_16x16x32_bf16 v[42:45], v[168:171], v[202:205], v[42:45]
	v_mfma_f32_16x16x32_bf16 v[30:33], v[160:163], v[210:213], v[30:33]
	v_mfma_f32_16x16x32_bf16 v[26:29], v[168:171], v[210:213], v[26:29]
	v_mfma_f32_16x16x32_bf16 v[14:17], v[160:163], v[218:221], v[14:17]
	v_mfma_f32_16x16x32_bf16 v[10:13], v[168:171], v[218:221], v[10:13]
	s_setprio 0
	s_setprio 1
	v_mfma_f32_16x16x32_bf16 v[54:57], v[172:175], v[190:193], v[54:57]
	v_mfma_f32_16x16x32_bf16 v[50:53], v[182:185], v[190:193], v[50:53]
	v_mfma_f32_16x16x32_bf16 v[38:41], v[172:175], v[198:201], v[38:41]
	v_mfma_f32_16x16x32_bf16 v[34:37], v[182:185], v[198:201], v[34:37]
	v_mfma_f32_16x16x32_bf16 v[22:25], v[172:175], v[206:209], v[22:25]
	v_mfma_f32_16x16x32_bf16 v[18:21], v[182:185], v[206:209], v[18:21]
	v_mfma_f32_16x16x32_bf16 v[6:9], v[172:175], v[214:217], v[6:9]
	v_mfma_f32_16x16x32_bf16 v[2:5], v[182:185], v[214:217], v[2:5]
	v_mfma_f32_16x16x32_bf16 v[54:57], v[176:179], v[194:197], v[54:57]
	v_mfma_f32_16x16x32_bf16 v[50:53], v[186:189], v[194:197], v[50:53]
	v_mfma_f32_16x16x32_bf16 v[38:41], v[176:179], v[202:205], v[38:41]
	v_mfma_f32_16x16x32_bf16 v[34:37], v[186:189], v[202:205], v[34:37]
	v_mfma_f32_16x16x32_bf16 v[22:25], v[176:179], v[210:213], v[22:25]
	v_mfma_f32_16x16x32_bf16 v[18:21], v[186:189], v[210:213], v[18:21]
	v_mfma_f32_16x16x32_bf16 v[6:9], v[176:179], v[218:221], v[6:9]
	v_mfma_f32_16x16x32_bf16 v[2:5], v[186:189], v[218:221], v[2:5]
	s_setprio 0
	s_barrier
	s_add_u32 s34, s34, 0x100
	s_addc_u32 s35, s35, 0
	s_add_u32 s2, s2, 0x100
	s_addc_u32 s54, s54, 0
	s_cmp_ge_i32 s59, s57
	s_mov_b32 s33, s59
	s_cbranch_scc0 .LBB0_1130

; #define PG8_STAGE(bufoff, gbase, voff) do { _Pragma("unroll") for (int _i = 0; _i < 2; ++_i) \
;         __builtin_amdgcn_global_load_lds((const unsigned*)((const char*)(gbase) + (voff)[_i]), (PG8_LAS unsigned*)(lds + (bufoff) + ldsw + _i * 8192), 16, 0, 0); } while (0)
; #define PG8_LDA(dst, b, h) do { _Pragma("unroll") for (int m = 0; m < 4; ++m) _Pragma("unroll") for (int k = 0; k < 2; ++k) dst[m][k] = *(const PG8_LAS bf16x8*)(lds + PG8_SA(b, h) + aoff + m * 2048 + k * 1024); } while (0)
; #define PG8_LDB(dst, b, h) do { _Pragma("unroll") for (int n = 0; n < 2; ++n) _Pragma("unroll") for (int k = 0; k < 2; ++k) dst[n][k] = *(const PG8_LAS bf16x8*)(lds + PG8_SB(b, h) + boff + n * 2048 + k * 1024); } while (0)
; #define PG8_MMA(ai, bj, At, Bt) do { __builtin_amdgcn_s_setprio(1); _Pragma("unroll") for (int m = 0; m < 4; ++m) _Pragma("unroll") for (int n = 0; n < 2; ++n) _Pragma("unroll") for (int k = 0; k < 2; ++k) \
;         acc[ai][bj][m][n] = __builtin_amdgcn_mfma_f32_16x16x32_bf16(Bt[n][k], At[m][k], acc[ai][bj][m][n], 0, 0, 0); __builtin_amdgcn_s_setprio(0); } while (0)
; #define PG8_WAIT_V(n) asm volatile("s_waitcnt vmcnt(" #n ")" ::: "memory")
; #define PG8_WAIT_L(n) asm volatile("s_waitcnt lgkmcnt(" #n ")" ::: "memory")
; template <class Epi, class Sched, bool ALIGN_EPI = false, bool SP2 = false>
; __device__ __forceinline__ void gemm_phase(PG8_LAS unsigned char* lds, const Gemm g, const Sched& S, const Epi& E) {
;     ...
;             const bool last = (t == nt - 2);
;             const char* a1 = cA + (size_t)(t + 1) * kstep;
;             const char* a2 = last ? nA : cA + (size_t)(t + 2) * kstep; const char* b2 = last ? nB : cB + (size_t)(t + 2) * kstep;
;             const char* a3 = a2 + kstep; const char* b3 = b2 + kstep;
;             if (last && has_next) S.a_ready(nxt);
;             if constexpr (SP2) {
;             PG8_LDB(B0, 0, 0); PG8_LDB(B1, 0, 1); PG8_SCHED; PG8_LDA(At, 0, 0); PG8_STAGE(PG8_SA(1, 1), a1 + hstep, voffA);
;             PG8_WAIT_V(8); PG8_WAIT_L(0); PG8_BAR; PG8_MMA(0, 0, At, B0); PG8_MMA(0, 1, At, B1); PG8_BAR; PG8_SCHED;
;             PG8_LDA(At, 0, 1); PG8_STAGE(PG8_SB(0, 0), b2, voffB); PG8_STAGE(PG8_SB(0, 1), b2 + hstep, voffB); PG8_STAGE(PG8_SA(0, 0), a2, voffA);
;             PG8_WAIT_V(8); PG8_WAIT_L(0); PG8_BAR; PG8_MMA(1, 0, At, B0); PG8_MMA(1, 1, At, B1); PG8_BAR; PG8_SCHED;
.LBB0_1222:
	s_add_i32 s59, s33, 2
	s_add_u32 s6, s38, 0x80
	s_addc_u32 s7, s39, 0
	s_add_i32 s72, 0, 0x10000
	s_cmp_eq_u32 s54, s33
	s_cselect_b32 s41, s13, s7
	s_cselect_b32 s40, s12, s6
	s_cselect_b32 s7, s37, s81
	s_cselect_b32 s6, s36, s80
	s_add_i32 s33, 0, 0x14000
	v_add_u32_e32 v166, s72, v148
	v_add_u32_e32 v178, s33, v148
	ds_read_b128 v[144:147], v166
	ds_read_b128 v[158:161], v166 offset:1024
	ds_read_b128 v[162:165], v166 offset:2048
	ds_read_b128 v[166:169], v166 offset:3072
	ds_read_b128 v[170:173], v178
	ds_read_b128 v[174:177], v178 offset:1024
	ds_read_b128 v[182:185], v178 offset:2048
	ds_read_b128 v[186:189], v178 offset:3072
	s_add_i32 m0, s45, 0xc000
	ds_read_b128 v[190:193], v151
	ds_read_b128 v[194:197], v151 offset:1024
	ds_read_b128 v[198:201], v151 offset:2048
	ds_read_b128 v[202:205], v151 offset:3072
	ds_read_b128 v[206:209], v151 offset:4096
	ds_read_b128 v[210:213], v151 offset:5120
	ds_read_b128 v[214:217], v151 offset:6144
	ds_read_b128 v[218:221], v151 offset:7168
	global_load_lds_dwordx4 v140, s[38:39]
	s_add_i32 m0, s45, 0xe000
	s_nop 0
	global_load_lds_dwordx4 v142, s[38:39]
	s_waitcnt vmcnt(8)
	s_waitcnt lgkmcnt(0)
	s_barrier
	s_setprio 1
	s_waitcnt lgkmcnt(0)
	v_mfma_f32_16x16x32_bf16 v[126:129], v[144:147], v[190:193], v[126:129]
	v_mfma_f32_16x16x32_bf16 v[122:125], v[162:165], v[190:193], v[122:125]
	v_mfma_f32_16x16x32_bf16 v[110:113], v[144:147], v[198:201], v[110:113]
	v_mfma_f32_16x16x32_bf16 v[106:109], v[162:165], v[198:201], v[106:109]
	v_mfma_f32_16x16x32_bf16 v[94:97], v[144:147], v[206:209], v[94:97]
	v_mfma_f32_16x16x32_bf16 v[90:93], v[162:165], v[206:209], v[90:93]
	v_mfma_f32_16x16x32_bf16 v[78:81], v[144:147], v[214:217], v[78:81]
	v_mfma_f32_16x16x32_bf16 v[74:77], v[162:165], v[214:217], v[74:77]
	v_mfma_f32_16x16x32_bf16 v[126:129], v[158:161], v[194:197], v[126:129]
	v_mfma_f32_16x16x32_bf16 v[122:125], v[166:169], v[194:197], v[122:125]
	v_mfma_f32_16x16x32_bf16 v[110:113], v[158:161], v[202:205], v[110:113]
	v_mfma_f32_16x16x32_bf16 v[106:109], v[166:169], v[202:205], v[106:109]
	v_mfma_f32_16x16x32_bf16 v[94:97], v[158:161], v[210:213], v[94:97]
	v_mfma_f32_16x16x32_bf16 v[90:93], v[166:169], v[210:213], v[90:93]
	v_mfma_f32_16x16x32_bf16 v[78:81], v[158:161], v[218:221], v[78:81]
	v_mfma_f32_16x16x32_bf16 v[74:77], v[166:169], v[218:221], v[74:77]
	s_setprio 0
	s_setprio 1
	v_mfma_f32_16x16x32_bf16 v[118:121], v[170:173], v[190:193], v[118:121]
	v_mfma_f32_16x16x32_bf16 v[114:117], v[182:185], v[190:193], v[114:117]
	v_mfma_f32_16x16x32_bf16 v[102:105], v[170:173], v[198:201], v[102:105]
	v_mfma_f32_16x16x32_bf16 v[98:101], v[182:185], v[198:201], v[98:101]
	v_mfma_f32_16x16x32_bf16 v[86:89], v[170:173], v[206:209], v[86:89]
	v_mfma_f32_16x16x32_bf16 v[82:85], v[182:185], v[206:209], v[82:85]
	v_mfma_f32_16x16x32_bf16 v[70:73], v[170:173], v[214:217], v[70:73]
	v_mfma_f32_16x16x32_bf16 v[66:69], v[182:185], v[214:217], v[66:69]
	v_mfma_f32_16x16x32_bf16 v[118:121], v[174:177], v[194:197], v[118:121]
	v_mfma_f32_16x16x32_bf16 v[114:117], v[186:189], v[194:197], v[114:117]
	v_mfma_f32_16x16x32_bf16 v[102:105], v[174:177], v[202:205], v[102:105]
	v_mfma_f32_16x16x32_bf16 v[98:101], v[186:189], v[202:205], v[98:101]
	v_mfma_f32_16x16x32_bf16 v[86:89], v[174:177], v[210:213], v[86:89]
	v_mfma_f32_16x16x32_bf16 v[82:85], v[186:189], v[210:213], v[82:85]
	v_mfma_f32_16x16x32_bf16 v[70:73], v[174:177], v[218:221], v[70:73]
	v_mfma_f32_16x16x32_bf16 v[66:69], v[186:189], v[218:221], v[66:69]
	s_setprio 0
	s_barrier
	s_add_i32 s72, s72, s44
	s_mov_b32 m0, s72
	ds_read_b128 v[190:193], v151 offset:16384
	ds_read_b128 v[194:197], v151 offset:17408
	ds_read_b128 v[198:201], v151 offset:18432
	ds_read_b128 v[202:205], v151 offset:19456
	ds_read_b128 v[206:209], v151 offset:20480
	ds_read_b128 v[210:213], v151 offset:21504
	ds_read_b128 v[214:217], v151 offset:22528
	ds_read_b128 v[218:221], v151 offset:23552
	global_load_lds_dwordx4 v132, s[6:7]
	s_add_i32 m0, s72, 0x2000
	s_add_u32 s100, s6, 0x80
	s_addc_u32 s101, s7, 0
	global_load_lds_dwordx4 v136, s[6:7]
	s_add_u32 s6, s6, s20
	s_addc_u32 s7, s7, s21
	s_add_i32 s33, s33, s44
	s_mov_b32 m0, s33
	s_nop 0
	global_load_lds_dwordx4 v132, s[6:7]
	s_add_i32 m0, s33, 0x2000
	s_nop 0
	global_load_lds_dwordx4 v136, s[6:7]
	s_mov_b32 m0, s45
	s_nop 0
	global_load_lds_dwordx4 v130, s[40:41]
	s_mov_b32 m0, s46
	s_nop 0
	global_load_lds_dwordx4 v134, s[40:41]
	s_waitcnt vmcnt(8)
	s_waitcnt lgkmcnt(0)
	s_barrier
	s_setprio 1
	s_waitcnt lgkmcnt(0)
	v_mfma_f32_16x16x32_bf16 v[62:65], v[144:147], v[190:193], v[62:65]
	v_mfma_f32_16x16x32_bf16 v[58:61], v[162:165], v[190:193], v[58:61]
	v_mfma_f32_16x16x32_bf16 v[46:49], v[144:147], v[198:201], v[46:49]
	v_mfma_f32_16x16x32_bf16 v[42:45], v[162:165], v[198:201], v[42:45]
	v_mfma_f32_16x16x32_bf16 v[30:33], v[144:147], v[206:209], v[30:33]
	v_mfma_f32_16x16x32_bf16 v[26:29], v[162:165], v[206:209], v[26:29]
	v_mfma_f32_16x16x32_bf16 v[14:17], v[144:147], v[214:217], v[14:17]
	v_mfma_f32_16x16x32_bf16 v[10:13], v[162:165], v[214:217], v[10:13]
	v_mfma_f32_16x16x32_bf16 v[62:65], v[158:161], v[194:197], v[62:65]
	v_mfma_f32_16x16x32_bf16 v[58:61], v[166:169], v[194:197], v[58:61]
	v_mfma_f32_16x16x32_bf16 v[46:49], v[158:161], v[202:205], v[46:49]
	v_mfma_f32_16x16x32_bf16 v[42:45], v[166:169], v[202:205], v[42:45]
	v_mfma_f32_16x16x32_bf16 v[30:33], v[158:161], v[210:213], v[30:33]
	v_mfma_f32_16x16x32_bf16 v[26:29], v[166:169], v[210:213], v[26:29]
	v_mfma_f32_16x16x32_bf16 v[14:17], v[158:161], v[218:221], v[14:17]
	v_mfma_f32_16x16x32_bf16 v[10:13], v[166:169], v[218:221], v[10:13]
	s_setprio 0
	s_setprio 1
	v_mfma_f32_16x16x32_bf16 v[54:57], v[170:173], v[190:193], v[54:57]
	v_mfma_f32_16x16x32_bf16 v[50:53], v[182:185], v[190:193], v[50:53]
	v_mfma_f32_16x16x32_bf16 v[38:41], v[170:173], v[198:201], v[38:41]
	v_mfma_f32_16x16x32_bf16 v[34:37], v[182:185], v[198:201], v[34:37]
	v_mfma_f32_16x16x32_bf16 v[22:25], v[170:173], v[206:209], v[22:25]
	v_mfma_f32_16x16x32_bf16 v[18:21], v[182:185], v[206:209], v[18:21]
	v_mfma_f32_16x16x32_bf16 v[6:9], v[170:173], v[214:217], v[6:9]
	v_mfma_f32_16x16x32_bf16 v[2:5], v[182:185], v[214:217], v[2:5]
	v_mfma_f32_16x16x32_bf16 v[54:57], v[174:177], v[194:197], v[54:57]
	v_mfma_f32_16x16x32_bf16 v[50:53], v[186:189], v[194:197], v[50:53]
	v_mfma_f32_16x16x32_bf16 v[38:41], v[174:177], v[202:205], v[38:41]
	v_mfma_f32_16x16x32_bf16 v[34:37], v[186:189], v[202:205], v[34:37]
	v_mfma_f32_16x16x32_bf16 v[22:25], v[174:177], v[210:213], v[22:25]
	v_mfma_f32_16x16x32_bf16 v[18:21], v[186:189], v[210:213], v[18:21]
	v_mfma_f32_16x16x32_bf16 v[6:9], v[174:177], v[218:221], v[6:9]
	v_mfma_f32_16x16x32_bf16 v[2:5], v[186:189], v[218:221], v[2:5]
	s_setprio 0
	s_barrier
; #define PG8_STAGE(bufoff, gbase, voff) do { _Pragma("unroll") for (int _i = 0; _i < 2; ++_i) \
;         __builtin_amdgcn_global_load_lds((const unsigned*)((const char*)(gbase) + (voff)[_i]), (PG8_LAS unsigned*)(lds + (bufoff) + ldsw + _i * 8192), 16, 0, 0); } while (0)
; #define PG8_LDA(dst, b, h) do { _Pragma("unroll") for (int m = 0; m < 4; ++m) _Pragma("unroll") for (int k = 0; k < 2; ++k) dst[m][k] = *(const PG8_LAS bf16x8*)(lds + PG8_SA(b, h) + aoff + m * 2048 + k * 1024); } while (0)
; #define PG8_LDB(dst, b, h) do { _Pragma("unroll") for (int n = 0; n < 2; ++n) _Pragma("unroll") for (int k = 0; k < 2; ++k) dst[n][k] = *(const PG8_LAS bf16x8*)(lds + PG8_SB(b, h) + boff + n * 2048 + k * 1024); } while (0)
; #define PG8_MMA(ai, bj, At, Bt) do { __builtin_amdgcn_s_setprio(1); _Pragma("unroll") for (int m = 0; m < 4; ++m) _Pragma("unroll") for (int n = 0; n < 2; ++n) _Pragma("unroll") for (int k = 0; k < 2; ++k) \
;         acc[ai][bj][m][n] = __builtin_amdgcn_mfma_f32_16x16x32_bf16(Bt[n][k], At[m][k], acc[ai][bj][m][n], 0, 0, 0); __builtin_amdgcn_s_setprio(0); } while (0)
; #define PG8_WAIT_V(n) asm volatile("s_waitcnt vmcnt(" #n ")" ::: "memory")
; #define PG8_WAIT_L(n) asm volatile("s_waitcnt lgkmcnt(" #n ")" ::: "memory")
; #define PG8_BAR __builtin_amdgcn_s_barrier()
; #define PG8_SCHED __builtin_amdgcn_sched_barrier(0)
; template <class Epi, class Sched, bool ALIGN_EPI = false, bool SP2 = false>
; __device__ __forceinline__ void gemm_phase(PG8_LAS unsigned char* lds, const Gemm g, const Sched& S, const Epi& E) {
;     ...
;             PG8_LDB(B0, 1, 0); PG8_LDB(B1, 1, 1); PG8_SCHED; PG8_LDA(At, 1, 0); PG8_STAGE(PG8_SA(0, 1), a2 + hstep, voffA);
;             PG8_WAIT_V(8); PG8_WAIT_L(0); PG8_BAR; PG8_MMA(0, 0, At, B0); PG8_MMA(0, 1, At, B1); PG8_BAR; PG8_SCHED;
;             PG8_LDA(At, 1, 1); PG8_STAGE(PG8_SB(1, 0), b3, voffB); PG8_STAGE(PG8_SB(1, 1), b3 + hstep, voffB); PG8_STAGE(PG8_SA(1, 0), a3, voffA);
;             PG8_WAIT_V(8); PG8_WAIT_L(0); PG8_BAR; PG8_MMA(1, 0, At, B0); PG8_MMA(1, 1, At, B1); PG8_BAR; PG8_SCHED;
	s_add_i32 s33, 0, 0x18000
	s_add_i32 s72, 0, 0x1c000
	v_add_u32_e32 v166, s33, v148
	v_add_u32_e32 v181, s72, v148
	ds_read_b128 v[144:147], v166
	ds_read_b128 v[158:161], v166 offset:1024
	ds_read_b128 v[162:165], v166 offset:2048
	ds_read_b128 v[166:169], v166 offset:3072
	ds_read_b128 v[170:173], v181
	ds_read_b128 v[174:177], v181 offset:1024
	ds_read_b128 v[182:185], v181 offset:2048
	ds_read_b128 v[186:189], v181 offset:3072
	s_add_u32 s6, s40, s20
	s_addc_u32 s7, s41, s21
	s_mov_b32 m0, s47
	ds_read_b128 v[190:193], v151 offset:32768
	ds_read_b128 v[194:197], v151 offset:33792
	ds_read_b128 v[198:201], v151 offset:34816
	ds_read_b128 v[202:205], v151 offset:35840
	ds_read_b128 v[206:209], v151 offset:36864
	ds_read_b128 v[210:213], v151 offset:37888
	ds_read_b128 v[214:217], v151 offset:38912
	ds_read_b128 v[218:221], v151 offset:39936
	global_load_lds_dwordx4 v130, s[6:7]
	s_mov_b32 m0, s48
	s_nop 0
	global_load_lds_dwordx4 v134, s[6:7]
	s_waitcnt vmcnt(8)
	s_waitcnt lgkmcnt(0)
	s_barrier
	s_setprio 1
	s_waitcnt lgkmcnt(0)
	v_mfma_f32_16x16x32_bf16 v[126:129], v[144:147], v[190:193], v[126:129]
	v_mfma_f32_16x16x32_bf16 v[122:125], v[162:165], v[190:193], v[122:125]
	v_mfma_f32_16x16x32_bf16 v[110:113], v[144:147], v[198:201], v[110:113]
	v_mfma_f32_16x16x32_bf16 v[106:109], v[162:165], v[198:201], v[106:109]
	v_mfma_f32_16x16x32_bf16 v[94:97], v[144:147], v[206:209], v[94:97]
	v_mfma_f32_16x16x32_bf16 v[90:93], v[162:165], v[206:209], v[90:93]
	v_mfma_f32_16x16x32_bf16 v[78:81], v[144:147], v[214:217], v[78:81]
	v_mfma_f32_16x16x32_bf16 v[74:77], v[162:165], v[214:217], v[74:77]
	v_mfma_f32_16x16x32_bf16 v[126:129], v[158:161], v[194:197], v[126:129]
	v_mfma_f32_16x16x32_bf16 v[122:125], v[166:169], v[194:197], v[122:125]
	v_mfma_f32_16x16x32_bf16 v[110:113], v[158:161], v[202:205], v[110:113]
	v_mfma_f32_16x16x32_bf16 v[106:109], v[166:169], v[202:205], v[106:109]
	v_mfma_f32_16x16x32_bf16 v[94:97], v[158:161], v[210:213], v[94:97]
	v_mfma_f32_16x16x32_bf16 v[90:93], v[166:169], v[210:213], v[90:93]
	v_mfma_f32_16x16x32_bf16 v[78:81], v[158:161], v[218:221], v[78:81]
	v_mfma_f32_16x16x32_bf16 v[74:77], v[166:169], v[218:221], v[74:77]
	s_setprio 0
	s_setprio 1
	v_mfma_f32_16x16x32_bf16 v[118:121], v[170:173], v[190:193], v[118:121]
	v_mfma_f32_16x16x32_bf16 v[114:117], v[182:185], v[190:193], v[114:117]
	v_mfma_f32_16x16x32_bf16 v[102:105], v[170:173], v[198:201], v[102:105]
	v_mfma_f32_16x16x32_bf16 v[98:101], v[182:185], v[198:201], v[98:101]
	v_mfma_f32_16x16x32_bf16 v[86:89], v[170:173], v[206:209], v[86:89]
	v_mfma_f32_16x16x32_bf16 v[82:85], v[182:185], v[206:209], v[82:85]
	v_mfma_f32_16x16x32_bf16 v[70:73], v[170:173], v[214:217], v[70:73]
	v_mfma_f32_16x16x32_bf16 v[66:69], v[182:185], v[214:217], v[66:69]
	v_mfma_f32_16x16x32_bf16 v[118:121], v[174:177], v[194:197], v[118:121]
	v_mfma_f32_16x16x32_bf16 v[114:117], v[186:189], v[194:197], v[114:117]
	v_mfma_f32_16x16x32_bf16 v[102:105], v[174:177], v[202:205], v[102:105]
	v_mfma_f32_16x16x32_bf16 v[98:101], v[186:189], v[202:205], v[98:101]
	v_mfma_f32_16x16x32_bf16 v[86:89], v[174:177], v[210:213], v[86:89]
	v_mfma_f32_16x16x32_bf16 v[82:85], v[186:189], v[210:213], v[82:85]
	v_mfma_f32_16x16x32_bf16 v[70:73], v[174:177], v[218:221], v[70:73]
	v_mfma_f32_16x16x32_bf16 v[66:69], v[186:189], v[218:221], v[66:69]
	s_setprio 0
	s_barrier
	s_add_i32 s6, s33, s44
	s_mov_b32 m0, s6
	ds_read_b128 v[190:193], v151 offset:49152
	ds_read_b128 v[194:197], v151 offset:50176
	ds_read_b128 v[198:201], v151 offset:51200
	ds_read_b128 v[202:205], v151 offset:52224
	ds_read_b128 v[206:209], v151 offset:53248
	ds_read_b128 v[210:213], v151 offset:54272
	ds_read_b128 v[214:217], v151 offset:55296
	ds_read_b128 v[218:221], v151 offset:56320
	global_load_lds_dwordx4 v132, s[100:101]
	s_add_i32 m0, s6, 0x2000
	s_add_i32 s6, s72, s44
	global_load_lds_dwordx4 v136, s[100:101]
	s_add_u32 s100, s100, s20
	s_addc_u32 s101, s101, s21
	s_mov_b32 m0, s6
	s_nop 0
	global_load_lds_dwordx4 v132, s[100:101]
	s_add_i32 m0, s6, 0x2000
	s_nop 0
	global_load_lds_dwordx4 v136, s[100:101]
	s_add_u32 s100, s40, 0x80
	s_addc_u32 s101, s41, 0
	s_mov_b32 m0, s50
	s_nop 0
	global_load_lds_dwordx4 v130, s[100:101]
	s_mov_b32 m0, s51
	s_nop 0
	global_load_lds_dwordx4 v134, s[100:101]
	s_waitcnt vmcnt(8)
	s_waitcnt lgkmcnt(0)
	s_barrier
	s_setprio 1
	s_waitcnt lgkmcnt(0)
	v_mfma_f32_16x16x32_bf16 v[62:65], v[144:147], v[190:193], v[62:65]
	v_mfma_f32_16x16x32_bf16 v[58:61], v[162:165], v[190:193], v[58:61]
	v_mfma_f32_16x16x32_bf16 v[46:49], v[144:147], v[198:201], v[46:49]
	v_mfma_f32_16x16x32_bf16 v[42:45], v[162:165], v[198:201], v[42:45]
	v_mfma_f32_16x16x32_bf16 v[30:33], v[144:147], v[206:209], v[30:33]
	v_mfma_f32_16x16x32_bf16 v[26:29], v[162:165], v[206:209], v[26:29]
	v_mfma_f32_16x16x32_bf16 v[14:17], v[144:147], v[214:217], v[14:17]
	v_mfma_f32_16x16x32_bf16 v[10:13], v[162:165], v[214:217], v[10:13]
	v_mfma_f32_16x16x32_bf16 v[62:65], v[158:161], v[194:197], v[62:65]
	v_mfma_f32_16x16x32_bf16 v[58:61], v[166:169], v[194:197], v[58:61]
	v_mfma_f32_16x16x32_bf16 v[46:49], v[158:161], v[202:205], v[46:49]
	v_mfma_f32_16x16x32_bf16 v[42:45], v[166:169], v[202:205], v[42:45]
	v_mfma_f32_16x16x32_bf16 v[30:33], v[158:161], v[210:213], v[30:33]
	v_mfma_f32_16x16x32_bf16 v[26:29], v[166:169], v[210:213], v[26:29]
	v_mfma_f32_16x16x32_bf16 v[14:17], v[158:161], v[218:221], v[14:17]
	v_mfma_f32_16x16x32_bf16 v[10:13], v[166:169], v[218:221], v[10:13]
	s_setprio 0
	s_setprio 1
	v_mfma_f32_16x16x32_bf16 v[54:57], v[170:173], v[190:193], v[54:57]
	v_mfma_f32_16x16x32_bf16 v[50:53], v[182:185], v[190:193], v[50:53]
	v_mfma_f32_16x16x32_bf16 v[38:41], v[170:173], v[198:201], v[38:41]
	v_mfma_f32_16x16x32_bf16 v[34:37], v[182:185], v[198:201], v[34:37]
	v_mfma_f32_16x16x32_bf16 v[22:25], v[170:173], v[206:209], v[22:25]
	v_mfma_f32_16x16x32_bf16 v[18:21], v[182:185], v[206:209], v[18:21]
	v_mfma_f32_16x16x32_bf16 v[6:9], v[170:173], v[214:217], v[6:9]
	v_mfma_f32_16x16x32_bf16 v[2:5], v[182:185], v[214:217], v[2:5]
	v_mfma_f32_16x16x32_bf16 v[54:57], v[174:177], v[194:197], v[54:57]
	v_mfma_f32_16x16x32_bf16 v[50:53], v[186:189], v[194:197], v[50:53]
	v_mfma_f32_16x16x32_bf16 v[38:41], v[174:177], v[202:205], v[38:41]
	v_mfma_f32_16x16x32_bf16 v[34:37], v[186:189], v[202:205], v[34:37]
	v_mfma_f32_16x16x32_bf16 v[22:25], v[174:177], v[210:213], v[22:25]
	v_mfma_f32_16x16x32_bf16 v[18:21], v[186:189], v[210:213], v[18:21]
	v_mfma_f32_16x16x32_bf16 v[6:9], v[174:177], v[218:221], v[6:9]
	v_mfma_f32_16x16x32_bf16 v[2:5], v[186:189], v[218:221], v[2:5]
	s_setprio 0
	s_barrier
	s_add_u32 s38, s38, 0x100
	s_addc_u32 s39, s39, 0
	s_add_u32 s80, s80, 0x100
	s_addc_u32 s81, s81, 0
	s_cmp_ge_i32 s59, s49
	s_mov_b32 s33, s59
	s_cbranch_scc0 .LBB0_1222
